# v50 (GEMM-loop s_nop trimmed) + removed 16 redundant s_waitcnt lgkmcnt(0) after the phase barrier in the GEMM K-loops
# baseline (speedup 1.0000x reference)
; #define PG8_STAGE(bufoff, gbase, voff) do { _Pragma("unroll") for (int _i = 0; _i < 2; ++_i) \
;         __builtin_amdgcn_global_load_lds((const unsigned*)((const char*)(gbase) + (voff)[_i]), (LAS unsigned*)(lds + (bufoff) + ldsw + _i * 8192), 16, 0, 0); } while (0)
; #define PG8_LDA(dst, b, h) do { _Pragma("unroll") for (int m = 0; m < 4; ++m) _Pragma("unroll") for (int k = 0; k < 2; ++k) dst[m][k] = *(const LAS bf16x8*)(lds + PG8_SA(b, h) + aoff + m * 2048 + k * 1024); } while (0)
; #define PG8_LDB(dst, b, h) do { _Pragma("unroll") for (int n = 0; n < 2; ++n) _Pragma("unroll") for (int k = 0; k < 2; ++k) dst[n][k] = *(const LAS bf16x8*)(lds + PG8_SB(b, h) + boff + n * 2048 + k * 1024); } while (0)
; #define PG8_MMA(ai, bj, At, Bt) do { __builtin_amdgcn_s_setprio(1); _Pragma("unroll") for (int m = 0; m < 4; ++m) _Pragma("unroll") for (int n = 0; n < 2; ++n) _Pragma("unroll") for (int k = 0; k < 2; ++k) \
;         acc[ai][bj][m][n] = __builtin_amdgcn_mfma_f32_16x16x32_bf16(Bt[n][k], At[m][k], acc[ai][bj][m][n], 0, 0, 0); __builtin_amdgcn_s_setprio(0); } while (0)
; #define PG8_WAIT_V(n) asm volatile("s_waitcnt vmcnt(" #n ")" ::: "memory")
; #define PG8_WAIT_L(n) asm volatile("s_waitcnt lgkmcnt(" #n ")" ::: "memory")
; #define PG8_BAR __builtin_amdgcn_s_barrier()
; template <class Epi>
; __device__ __forceinline__ void gemm_phase(LAS unsigned char* lds, const Gemm g, const StaticOrder& S, const Epi& E, const int tid) {
;     ...
;         for (int t = 0; t < nt; t += 2) {
;             const bool last = (t == nt - 2);
;             const char* a1 = cA + (size_t)(t + 1) * kstep + ((t + 1) >= 8 ? xtra : 0);
;             const char* a2 = last ? nA : cA + (size_t)(t + 2) * kstep + ((t + 2) >= 8 ? xtra : 0); const char* b2 = last ? nB : cB + (size_t)(t + 2) * kstep;
;             const char* a3 = a2 + kstep; const char* b3 = b2 + kstep;
;             PG8_LDB(B0, 0, 0); PG8_LDB(B1, 0, 1); PG8_SCHED; PG8_LDA(At, 0, 0); PG8_STAGE(PG8_SA(1, 1), a1 + hstepA, voffA);
;             PG8_WAIT_V(8); PG8_WAIT_L(0); PG8_BAR; PG8_MMA(0, 0, At, B0); PG8_MMA(0, 1, At, B1); PG8_BAR; PG8_SCHED;
;             PG8_LDA(At, 0, 1); PG8_STAGE(PG8_SB(0, 0), b2, voffB); PG8_STAGE(PG8_SB(0, 1), b2 + hstepB, voffB); PG8_STAGE(PG8_SA(0, 0), a2, voffA);
;             PG8_WAIT_V(8); PG8_WAIT_L(0); PG8_BAR; PG8_MMA(1, 0, At, B0); PG8_MMA(1, 1, At, B1); PG8_BAR; PG8_SCHED;
.LBB0_160:
	s_add_u32 s42, s94, 0x100
	s_addc_u32 s43, s95, 0
	s_add_i32 s8, 0, 0x10000
	v_add_u32_e32 v142, s8, v245
	v_add_u32_e32 v158, s15, v245
	ds_read_b128 v[122:125], v142
	ds_read_b128 v[126:129], v142 offset:1024
	ds_read_b128 v[138:141], v142 offset:2048
	ds_read_b128 v[142:145], v142 offset:3072
	ds_read_b128 v[146:149], v158
	ds_read_b128 v[150:153], v158 offset:1024
	ds_read_b128 v[154:157], v158 offset:2048
	ds_read_b128 v[158:161], v158 offset:3072
	s_cmp_eq_u32 s89, 12
	s_cselect_b32 vcc_hi, s91, s43
	s_cselect_b32 vcc_lo, s90, s42
	s_cselect_b32 s93, s36, s46
	s_cselect_b32 s92, s37, s45
	v_lshl_add_u64 v[210:211], s[94:95], 0, v[206:207]
	s_add_i32 m0, s19, 0xc000
	ds_read_b128 v[162:165], v246
	ds_read_b128 v[166:169], v246 offset:1024
	ds_read_b128 v[170:173], v246 offset:2048
	ds_read_b128 v[174:177], v246 offset:3072
	ds_read_b128 v[178:181], v246 offset:4096
	ds_read_b128 v[182:185], v246 offset:5120
	ds_read_b128 v[186:189], v246 offset:6144
	ds_read_b128 v[190:193], v246 offset:7168
	global_load_lds_dwordx4 v[210:211], off
	v_lshl_add_u64 v[210:211], s[94:95], 0, v[208:209]
	s_add_i32 m0, s19, 0xe000
	s_nop 0
	global_load_lds_dwordx4 v[210:211], off
	s_waitcnt vmcnt(8)
	s_waitcnt lgkmcnt(0)
	s_barrier
	s_setprio 1
	v_mfma_f32_16x16x32_bf16 v[134:137], v[122:125], v[162:165], v[134:137]
	v_mfma_f32_16x16x32_bf16 v[130:133], v[138:141], v[162:165], v[130:133]
	v_mfma_f32_16x16x32_bf16 v[108:111], v[122:125], v[170:173], v[108:111]
	v_mfma_f32_16x16x32_bf16 v[104:107], v[138:141], v[170:173], v[104:107]
	v_mfma_f32_16x16x32_bf16 v[92:95], v[122:125], v[178:181], v[92:95]
	v_mfma_f32_16x16x32_bf16 v[88:91], v[138:141], v[178:181], v[88:91]
	v_mfma_f32_16x16x32_bf16 v[76:79], v[122:125], v[186:189], v[76:79]
	v_mfma_f32_16x16x32_bf16 v[72:75], v[138:141], v[186:189], v[72:75]
	v_mfma_f32_16x16x32_bf16 v[134:137], v[126:129], v[166:169], v[134:137]
	v_mfma_f32_16x16x32_bf16 v[130:133], v[142:145], v[166:169], v[130:133]
	v_mfma_f32_16x16x32_bf16 v[108:111], v[126:129], v[174:177], v[108:111]
	v_mfma_f32_16x16x32_bf16 v[104:107], v[142:145], v[174:177], v[104:107]
	v_mfma_f32_16x16x32_bf16 v[92:95], v[126:129], v[182:185], v[92:95]
	v_mfma_f32_16x16x32_bf16 v[88:91], v[142:145], v[182:185], v[88:91]
	v_mfma_f32_16x16x32_bf16 v[76:79], v[126:129], v[190:193], v[76:79]
	v_mfma_f32_16x16x32_bf16 v[72:75], v[142:145], v[190:193], v[72:75]
	v_mfma_f32_16x16x32_bf16 v[118:121], v[146:149], v[162:165], v[118:121]
	v_mfma_f32_16x16x32_bf16 v[114:117], v[154:157], v[162:165], v[114:117]
	v_mfma_f32_16x16x32_bf16 v[100:103], v[146:149], v[170:173], v[100:103]
	v_mfma_f32_16x16x32_bf16 v[96:99], v[154:157], v[170:173], v[96:99]
	v_mfma_f32_16x16x32_bf16 v[84:87], v[146:149], v[178:181], v[84:87]
	v_mfma_f32_16x16x32_bf16 v[80:83], v[154:157], v[178:181], v[80:83]
	v_mfma_f32_16x16x32_bf16 v[68:71], v[146:149], v[186:189], v[68:71]
	v_mfma_f32_16x16x32_bf16 v[64:67], v[154:157], v[186:189], v[64:67]
	v_mfma_f32_16x16x32_bf16 v[118:121], v[150:153], v[166:169], v[118:121]
	v_mfma_f32_16x16x32_bf16 v[114:117], v[158:161], v[166:169], v[114:117]
	v_mfma_f32_16x16x32_bf16 v[100:103], v[150:153], v[174:177], v[100:103]
	v_mfma_f32_16x16x32_bf16 v[96:99], v[158:161], v[174:177], v[96:99]
	v_mfma_f32_16x16x32_bf16 v[84:87], v[150:153], v[182:185], v[84:87]
	v_mfma_f32_16x16x32_bf16 v[80:83], v[158:161], v[182:185], v[80:83]
	v_mfma_f32_16x16x32_bf16 v[68:71], v[150:153], v[190:193], v[68:71]
	v_mfma_f32_16x16x32_bf16 v[64:67], v[158:161], v[190:193], v[64:67]
	s_setprio 0
	s_barrier
	s_add_i32 s8, s8, s11
	v_lshl_add_u64 v[210:211], s[92:93], 0, v[112:113]
	s_mov_b32 m0, s8
	ds_read_b128 v[162:165], v246 offset:16384
	ds_read_b128 v[166:169], v246 offset:17408
	ds_read_b128 v[170:173], v246 offset:18432
	ds_read_b128 v[174:177], v246 offset:19456
	ds_read_b128 v[178:181], v246 offset:20480
	ds_read_b128 v[182:185], v246 offset:21504
	ds_read_b128 v[186:189], v246 offset:22528
	ds_read_b128 v[190:193], v246 offset:23552
	global_load_lds_dwordx4 v112, s[92:93]
	s_add_i32 m0, s8, 0x2000
	s_add_u32 s8, s92, 0x40000
	v_lshl_add_u64 v[212:213], s[92:93], 0, v[200:201]
	s_addc_u32 s9, s93, 0
	s_add_i32 s13, s15, s11
	global_load_lds_dwordx4 v200, s[92:93]
	s_mov_b32 m0, s13
	s_nop 0
	global_load_lds_dwordx4 v112, s[8:9]
	s_add_i32 m0, s13, 0x2000
	s_nop 0
	global_load_lds_dwordx4 v200, s[8:9]
	s_mov_b32 m0, s19
	s_nop 0
	global_load_lds_dwordx4 v202, vcc
	s_mov_b32 m0, s28
	s_nop 0
	global_load_lds_dwordx4 v204, vcc
	s_waitcnt vmcnt(8)
	s_waitcnt lgkmcnt(0)
	s_barrier
; #define PG8_STAGE(bufoff, gbase, voff) do { _Pragma("unroll") for (int _i = 0; _i < 2; ++_i) \
;         __builtin_amdgcn_global_load_lds((const unsigned*)((const char*)(gbase) + (voff)[_i]), (LAS unsigned*)(lds + (bufoff) + ldsw + _i * 8192), 16, 0, 0); } while (0)
; #define PG8_LDA(dst, b, h) do { _Pragma("unroll") for (int m = 0; m < 4; ++m) _Pragma("unroll") for (int k = 0; k < 2; ++k) dst[m][k] = *(const LAS bf16x8*)(lds + PG8_SA(b, h) + aoff + m * 2048 + k * 1024); } while (0)
; #define PG8_LDB(dst, b, h) do { _Pragma("unroll") for (int n = 0; n < 2; ++n) _Pragma("unroll") for (int k = 0; k < 2; ++k) dst[n][k] = *(const LAS bf16x8*)(lds + PG8_SB(b, h) + boff + n * 2048 + k * 1024); } while (0)
; #define PG8_MMA(ai, bj, At, Bt) do { __builtin_amdgcn_s_setprio(1); _Pragma("unroll") for (int m = 0; m < 4; ++m) _Pragma("unroll") for (int n = 0; n < 2; ++n) _Pragma("unroll") for (int k = 0; k < 2; ++k) \
;         acc[ai][bj][m][n] = __builtin_amdgcn_mfma_f32_16x16x32_bf16(Bt[n][k], At[m][k], acc[ai][bj][m][n], 0, 0, 0); __builtin_amdgcn_s_setprio(0); } while (0)
; #define PG8_WAIT_V(n) asm volatile("s_waitcnt vmcnt(" #n ")" ::: "memory")
; #define PG8_WAIT_L(n) asm volatile("s_waitcnt lgkmcnt(" #n ")" ::: "memory")
; #define PG8_BAR __builtin_amdgcn_s_barrier()
; #define PG8_SCHED __builtin_amdgcn_sched_barrier(0)
; template <class Epi>
; __device__ __forceinline__ void gemm_phase(LAS unsigned char* lds, const Gemm g, const StaticOrder& S, const Epi& E, const int tid) {
;     ...
;             PG8_WAIT_V(8); PG8_WAIT_L(0); PG8_BAR; PG8_MMA(1, 0, At, B0); PG8_MMA(1, 1, At, B1); PG8_BAR; PG8_SCHED;
;             PG8_LDB(B0, 1, 0); PG8_LDB(B1, 1, 1); PG8_SCHED; PG8_LDA(At, 1, 0); PG8_STAGE(PG8_SA(0, 1), a2 + hstepA, voffA);
;             PG8_WAIT_V(8); PG8_WAIT_L(0); PG8_BAR; PG8_MMA(0, 0, At, B0); PG8_MMA(0, 1, At, B1); PG8_BAR; PG8_SCHED;
	s_setprio 1
	v_mfma_f32_16x16x32_bf16 v[60:63], v[122:125], v[162:165], v[60:63]
	v_mfma_f32_16x16x32_bf16 v[56:59], v[138:141], v[162:165], v[56:59]
	v_mfma_f32_16x16x32_bf16 v[44:47], v[122:125], v[170:173], v[44:47]
	v_mfma_f32_16x16x32_bf16 v[40:43], v[138:141], v[170:173], v[40:43]
	v_mfma_f32_16x16x32_bf16 v[28:31], v[122:125], v[178:181], v[28:31]
	v_mfma_f32_16x16x32_bf16 v[24:27], v[138:141], v[178:181], v[24:27]
	v_mfma_f32_16x16x32_bf16 v[12:15], v[122:125], v[186:189], v[12:15]
	v_mfma_f32_16x16x32_bf16 v[8:11], v[138:141], v[186:189], v[8:11]
	v_mfma_f32_16x16x32_bf16 v[60:63], v[126:129], v[166:169], v[60:63]
	v_mfma_f32_16x16x32_bf16 v[56:59], v[142:145], v[166:169], v[56:59]
	v_mfma_f32_16x16x32_bf16 v[44:47], v[126:129], v[174:177], v[44:47]
	v_mfma_f32_16x16x32_bf16 v[40:43], v[142:145], v[174:177], v[40:43]
	v_mfma_f32_16x16x32_bf16 v[28:31], v[126:129], v[182:185], v[28:31]
	v_mfma_f32_16x16x32_bf16 v[24:27], v[142:145], v[182:185], v[24:27]
	v_mfma_f32_16x16x32_bf16 v[12:15], v[126:129], v[190:193], v[12:15]
	v_mfma_f32_16x16x32_bf16 v[8:11], v[142:145], v[190:193], v[8:11]
	v_mfma_f32_16x16x32_bf16 v[52:55], v[146:149], v[162:165], v[52:55]
	v_mfma_f32_16x16x32_bf16 v[48:51], v[154:157], v[162:165], v[48:51]
	v_mfma_f32_16x16x32_bf16 v[36:39], v[146:149], v[170:173], v[36:39]
	v_mfma_f32_16x16x32_bf16 v[32:35], v[154:157], v[170:173], v[32:35]
	v_mfma_f32_16x16x32_bf16 v[20:23], v[146:149], v[178:181], v[20:23]
	v_mfma_f32_16x16x32_bf16 v[16:19], v[154:157], v[178:181], v[16:19]
	v_mfma_f32_16x16x32_bf16 v[4:7], v[146:149], v[186:189], v[4:7]
	v_mfma_f32_16x16x32_bf16 v[0:3], v[154:157], v[186:189], v[0:3]
	v_mfma_f32_16x16x32_bf16 v[52:55], v[150:153], v[166:169], v[52:55]
	v_mfma_f32_16x16x32_bf16 v[48:51], v[158:161], v[166:169], v[48:51]
	v_mfma_f32_16x16x32_bf16 v[36:39], v[150:153], v[174:177], v[36:39]
	v_mfma_f32_16x16x32_bf16 v[32:35], v[158:161], v[174:177], v[32:35]
	v_mfma_f32_16x16x32_bf16 v[20:23], v[150:153], v[182:185], v[20:23]
	v_mfma_f32_16x16x32_bf16 v[16:19], v[158:161], v[182:185], v[16:19]
	v_mfma_f32_16x16x32_bf16 v[4:7], v[150:153], v[190:193], v[4:7]
	v_mfma_f32_16x16x32_bf16 v[0:3], v[158:161], v[190:193], v[0:3]
	s_setprio 0
	s_barrier
	s_add_i32 s13, 0, 0x18000
	s_add_i32 s31, 0, 0x1c000
	v_add_u32_e32 v142, s13, v245
	v_add_u32_e32 v158, s31, v245
	ds_read_b128 v[122:125], v142
	ds_read_b128 v[126:129], v142 offset:1024
	ds_read_b128 v[138:141], v142 offset:2048
	ds_read_b128 v[142:145], v142 offset:3072
	ds_read_b128 v[146:149], v158
	ds_read_b128 v[150:153], v158 offset:1024
	ds_read_b128 v[154:157], v158 offset:2048
	ds_read_b128 v[158:161], v158 offset:3072
	s_add_u32 s8, vcc_lo, 0xc0000
	s_addc_u32 s9, vcc_hi, 0
	s_mov_b32 m0, s30
	ds_read_b128 v[162:165], v246 offset:32768
	ds_read_b128 v[166:169], v246 offset:33792
	ds_read_b128 v[170:173], v246 offset:34816
	ds_read_b128 v[174:177], v246 offset:35840
	ds_read_b128 v[178:181], v246 offset:36864
	ds_read_b128 v[182:185], v246 offset:37888
	ds_read_b128 v[186:189], v246 offset:38912
	ds_read_b128 v[190:193], v246 offset:39936
	global_load_lds_dwordx4 v202, s[8:9]
	v_lshl_add_u64 v[248:249], s[8:9], 0, v[204:205]
	s_mov_b32 m0, s35
	s_nop 0
	global_load_lds_dwordx4 v204, s[8:9]
	s_waitcnt vmcnt(8)
	s_waitcnt lgkmcnt(0)
	s_barrier
	s_setprio 1
	v_mfma_f32_16x16x32_bf16 v[134:137], v[122:125], v[162:165], v[134:137]
	v_mfma_f32_16x16x32_bf16 v[130:133], v[138:141], v[162:165], v[130:133]
	v_mfma_f32_16x16x32_bf16 v[108:111], v[122:125], v[170:173], v[108:111]
	v_mfma_f32_16x16x32_bf16 v[104:107], v[138:141], v[170:173], v[104:107]
	v_mfma_f32_16x16x32_bf16 v[92:95], v[122:125], v[178:181], v[92:95]
	v_mfma_f32_16x16x32_bf16 v[88:91], v[138:141], v[178:181], v[88:91]
	v_mfma_f32_16x16x32_bf16 v[76:79], v[122:125], v[186:189], v[76:79]
	v_mfma_f32_16x16x32_bf16 v[72:75], v[138:141], v[186:189], v[72:75]
	v_mfma_f32_16x16x32_bf16 v[134:137], v[126:129], v[166:169], v[134:137]
	v_mfma_f32_16x16x32_bf16 v[130:133], v[142:145], v[166:169], v[130:133]
	v_mfma_f32_16x16x32_bf16 v[108:111], v[126:129], v[174:177], v[108:111]
	v_mfma_f32_16x16x32_bf16 v[104:107], v[142:145], v[174:177], v[104:107]
	v_mfma_f32_16x16x32_bf16 v[92:95], v[126:129], v[182:185], v[92:95]
	v_mfma_f32_16x16x32_bf16 v[88:91], v[142:145], v[182:185], v[88:91]
	v_mfma_f32_16x16x32_bf16 v[76:79], v[126:129], v[190:193], v[76:79]
	v_mfma_f32_16x16x32_bf16 v[72:75], v[142:145], v[190:193], v[72:75]
	v_mfma_f32_16x16x32_bf16 v[118:121], v[146:149], v[162:165], v[118:121]
	v_mfma_f32_16x16x32_bf16 v[114:117], v[154:157], v[162:165], v[114:117]
	v_mfma_f32_16x16x32_bf16 v[100:103], v[146:149], v[170:173], v[100:103]
	v_mfma_f32_16x16x32_bf16 v[96:99], v[154:157], v[170:173], v[96:99]
	v_mfma_f32_16x16x32_bf16 v[84:87], v[146:149], v[178:181], v[84:87]
	v_mfma_f32_16x16x32_bf16 v[80:83], v[154:157], v[178:181], v[80:83]
	v_mfma_f32_16x16x32_bf16 v[68:71], v[146:149], v[186:189], v[68:71]
	v_mfma_f32_16x16x32_bf16 v[64:67], v[154:157], v[186:189], v[64:67]
	v_mfma_f32_16x16x32_bf16 v[118:121], v[150:153], v[166:169], v[118:121]
	v_mfma_f32_16x16x32_bf16 v[114:117], v[158:161], v[166:169], v[114:117]
	v_mfma_f32_16x16x32_bf16 v[100:103], v[150:153], v[174:177], v[100:103]
	v_mfma_f32_16x16x32_bf16 v[96:99], v[158:161], v[174:177], v[96:99]
	v_mfma_f32_16x16x32_bf16 v[84:87], v[150:153], v[182:185], v[84:87]
	v_mfma_f32_16x16x32_bf16 v[80:83], v[158:161], v[182:185], v[80:83]
	v_mfma_f32_16x16x32_bf16 v[68:71], v[150:153], v[190:193], v[68:71]
	v_mfma_f32_16x16x32_bf16 v[64:67], v[158:161], v[190:193], v[64:67]
	s_setprio 0
	s_barrier
; #define PG8_STAGE(bufoff, gbase, voff) do { _Pragma("unroll") for (int _i = 0; _i < 2; ++_i) \
;         __builtin_amdgcn_global_load_lds((const unsigned*)((const char*)(gbase) + (voff)[_i]), (LAS unsigned*)(lds + (bufoff) + ldsw + _i * 8192), 16, 0, 0); } while (0)
; #define PG8_LDA(dst, b, h) do { _Pragma("unroll") for (int m = 0; m < 4; ++m) _Pragma("unroll") for (int k = 0; k < 2; ++k) dst[m][k] = *(const LAS bf16x8*)(lds + PG8_SA(b, h) + aoff + m * 2048 + k * 1024); } while (0)
; #define PG8_MMA(ai, bj, At, Bt) do { __builtin_amdgcn_s_setprio(1); _Pragma("unroll") for (int m = 0; m < 4; ++m) _Pragma("unroll") for (int n = 0; n < 2; ++n) _Pragma("unroll") for (int k = 0; k < 2; ++k) \
;         acc[ai][bj][m][n] = __builtin_amdgcn_mfma_f32_16x16x32_bf16(Bt[n][k], At[m][k], acc[ai][bj][m][n], 0, 0, 0); __builtin_amdgcn_s_setprio(0); } while (0)
; #define PG8_WAIT_V(n) asm volatile("s_waitcnt vmcnt(" #n ")" ::: "memory")
; #define PG8_WAIT_L(n) asm volatile("s_waitcnt lgkmcnt(" #n ")" ::: "memory")
; #define PG8_BAR __builtin_amdgcn_s_barrier()
; #define PG8_SCHED __builtin_amdgcn_sched_barrier(0)
; template <class Epi>
; __device__ __forceinline__ void gemm_phase(LAS unsigned char* lds, const Gemm g, const StaticOrder& S, const Epi& E, const int tid) {
;     ...
;             PG8_LDA(At, 1, 1); PG8_STAGE(PG8_SB(1, 0), b3, voffB); PG8_STAGE(PG8_SB(1, 1), b3 + hstepB, voffB); PG8_STAGE(PG8_SA(1, 0), a3, voffA);
;             PG8_WAIT_V(8); PG8_WAIT_L(0); PG8_BAR; PG8_MMA(1, 0, At, B0); PG8_MMA(1, 1, At, B1); PG8_BAR; PG8_SCHED;
;         }
;         if (wr == 0) PG8_BAR;
	s_add_i32 s8, s13, s11
	s_add_u32 s100, s92, 0x80
	s_addc_u32 s101, s93, 0
	s_mov_b32 m0, s8
	ds_read_b128 v[162:165], v246 offset:49152
	ds_read_b128 v[166:169], v246 offset:50176
	ds_read_b128 v[170:173], v246 offset:51200
	ds_read_b128 v[174:177], v246 offset:52224
	ds_read_b128 v[178:181], v246 offset:53248
	ds_read_b128 v[182:185], v246 offset:54272
	ds_read_b128 v[186:189], v246 offset:55296
	ds_read_b128 v[190:193], v246 offset:56320
	global_load_lds_dwordx4 v112, s[100:101]
	s_add_i32 m0, s8, 0x2000
	s_add_u32 s8, s92, 0x40080
	v_lshl_add_u64 v[210:211], v[212:213], 0, s[24:25]
	s_addc_u32 s9, s93, 0
	s_add_i32 s13, s31, s11
	global_load_lds_dwordx4 v[210:211], off
	s_mov_b32 m0, s13
	s_nop 0
	global_load_lds_dwordx4 v112, s[8:9]
	s_add_i32 m0, s13, 0x2000
	s_nop 0
	global_load_lds_dwordx4 v200, s[8:9]
	s_add_u32 s100, vcc_lo, 0x80
	s_addc_u32 s101, vcc_hi, 0
	s_mov_b32 m0, s38
	s_nop 0
	global_load_lds_dwordx4 v202, s[100:101]
	s_add_u32 s100, vcc_lo, 0x80
	s_addc_u32 s101, vcc_hi, 0
	s_mov_b32 m0, s39
	s_nop 0
	global_load_lds_dwordx4 v204, s[100:101]
	s_waitcnt vmcnt(8)
	s_waitcnt lgkmcnt(0)
	s_barrier
	s_setprio 1
	v_mfma_f32_16x16x32_bf16 v[60:63], v[122:125], v[162:165], v[60:63]
	v_mfma_f32_16x16x32_bf16 v[56:59], v[138:141], v[162:165], v[56:59]
	v_mfma_f32_16x16x32_bf16 v[44:47], v[122:125], v[170:173], v[44:47]
	v_mfma_f32_16x16x32_bf16 v[40:43], v[138:141], v[170:173], v[40:43]
	v_mfma_f32_16x16x32_bf16 v[28:31], v[122:125], v[178:181], v[28:31]
	v_mfma_f32_16x16x32_bf16 v[24:27], v[138:141], v[178:181], v[24:27]
	v_mfma_f32_16x16x32_bf16 v[12:15], v[122:125], v[186:189], v[12:15]
	v_mfma_f32_16x16x32_bf16 v[8:11], v[138:141], v[186:189], v[8:11]
	v_mfma_f32_16x16x32_bf16 v[60:63], v[126:129], v[166:169], v[60:63]
	v_mfma_f32_16x16x32_bf16 v[56:59], v[142:145], v[166:169], v[56:59]
	v_mfma_f32_16x16x32_bf16 v[44:47], v[126:129], v[174:177], v[44:47]
	v_mfma_f32_16x16x32_bf16 v[40:43], v[142:145], v[174:177], v[40:43]
	v_mfma_f32_16x16x32_bf16 v[28:31], v[126:129], v[182:185], v[28:31]
	v_mfma_f32_16x16x32_bf16 v[24:27], v[142:145], v[182:185], v[24:27]
	v_mfma_f32_16x16x32_bf16 v[12:15], v[126:129], v[190:193], v[12:15]
	v_mfma_f32_16x16x32_bf16 v[8:11], v[142:145], v[190:193], v[8:11]
	v_mfma_f32_16x16x32_bf16 v[52:55], v[146:149], v[162:165], v[52:55]
	v_mfma_f32_16x16x32_bf16 v[48:51], v[154:157], v[162:165], v[48:51]
	v_mfma_f32_16x16x32_bf16 v[36:39], v[146:149], v[170:173], v[36:39]
	v_mfma_f32_16x16x32_bf16 v[32:35], v[154:157], v[170:173], v[32:35]
	v_mfma_f32_16x16x32_bf16 v[20:23], v[146:149], v[178:181], v[20:23]
	v_mfma_f32_16x16x32_bf16 v[16:19], v[154:157], v[178:181], v[16:19]
	v_mfma_f32_16x16x32_bf16 v[4:7], v[146:149], v[186:189], v[4:7]
	v_mfma_f32_16x16x32_bf16 v[0:3], v[154:157], v[186:189], v[0:3]
	v_mfma_f32_16x16x32_bf16 v[52:55], v[150:153], v[166:169], v[52:55]
	v_mfma_f32_16x16x32_bf16 v[48:51], v[158:161], v[166:169], v[48:51]
	v_mfma_f32_16x16x32_bf16 v[36:39], v[150:153], v[174:177], v[36:39]
	v_mfma_f32_16x16x32_bf16 v[32:35], v[158:161], v[174:177], v[32:35]
	v_mfma_f32_16x16x32_bf16 v[20:23], v[150:153], v[182:185], v[20:23]
	v_mfma_f32_16x16x32_bf16 v[16:19], v[158:161], v[182:185], v[16:19]
	v_mfma_f32_16x16x32_bf16 v[4:7], v[150:153], v[190:193], v[4:7]
	v_mfma_f32_16x16x32_bf16 v[0:3], v[158:161], v[190:193], v[0:3]
	s_setprio 0
	s_barrier
	s_add_i32 s89, s89, 2
	s_add_u32 s45, s45, 0x100
	s_addc_u32 s46, s46, 0
	s_cmp_gt_u32 s89, 13
	s_mov_b64 s[94:95], s[42:43]
	s_cbranch_scc0 .LBB0_160
	s_and_b64 vcc, exec, s[86:87]
	s_cbranch_vccz .LBB0_163
	s_barrier

; #define PG8_STAGE(bufoff, gbase, voff) do { _Pragma("unroll") for (int _i = 0; _i < 2; ++_i) \
;         __builtin_amdgcn_global_load_lds((const unsigned*)((const char*)(gbase) + (voff)[_i]), (LAS unsigned*)(lds + (bufoff) + ldsw + _i * 8192), 16, 0, 0); } while (0)
; #define PG8_LDA(dst, b, h) do { _Pragma("unroll") for (int m = 0; m < 4; ++m) _Pragma("unroll") for (int k = 0; k < 2; ++k) dst[m][k] = *(const LAS bf16x8*)(lds + PG8_SA(b, h) + aoff + m * 2048 + k * 1024); } while (0)
; #define PG8_LDB(dst, b, h) do { _Pragma("unroll") for (int n = 0; n < 2; ++n) _Pragma("unroll") for (int k = 0; k < 2; ++k) dst[n][k] = *(const LAS bf16x8*)(lds + PG8_SB(b, h) + boff + n * 2048 + k * 1024); } while (0)
; #define PG8_MMA(ai, bj, At, Bt) do { __builtin_amdgcn_s_setprio(1); _Pragma("unroll") for (int m = 0; m < 4; ++m) _Pragma("unroll") for (int n = 0; n < 2; ++n) _Pragma("unroll") for (int k = 0; k < 2; ++k) \
;         acc[ai][bj][m][n] = __builtin_amdgcn_mfma_f32_16x16x32_bf16(Bt[n][k], At[m][k], acc[ai][bj][m][n], 0, 0, 0); __builtin_amdgcn_s_setprio(0); } while (0)
; #define PG8_WAIT_V(n) asm volatile("s_waitcnt vmcnt(" #n ")" ::: "memory")
; #define PG8_WAIT_L(n) asm volatile("s_waitcnt lgkmcnt(" #n ")" ::: "memory")
; #define PG8_BAR __builtin_amdgcn_s_barrier()
; template <class Epi>
; __device__ __forceinline__ void gemm_phase(LAS unsigned char* lds, const Gemm g, const StaticOrder& S, const Epi& E, const int tid) {
;     ...
;         for (int t = 0; t < nt; t += 2) {
;             const bool last = (t == nt - 2);
;             const char* a1 = cA + (size_t)(t + 1) * kstep + ((t + 1) >= 8 ? xtra : 0);
;             const char* a2 = last ? nA : cA + (size_t)(t + 2) * kstep + ((t + 2) >= 8 ? xtra : 0); const char* b2 = last ? nB : cB + (size_t)(t + 2) * kstep;
;             const char* a3 = a2 + kstep; const char* b3 = b2 + kstep;
;             PG8_LDB(B0, 0, 0); PG8_LDB(B1, 0, 1); PG8_SCHED; PG8_LDA(At, 0, 0); PG8_STAGE(PG8_SA(1, 1), a1 + hstepA, voffA);
;             PG8_WAIT_V(8); PG8_WAIT_L(0); PG8_BAR; PG8_MMA(0, 0, At, B0); PG8_MMA(0, 1, At, B1); PG8_BAR; PG8_SCHED;
;             PG8_LDA(At, 0, 1); PG8_STAGE(PG8_SB(0, 0), b2, voffB); PG8_STAGE(PG8_SB(0, 1), b2 + hstepB, voffB); PG8_STAGE(PG8_SA(0, 0), a2, voffA);
;             PG8_WAIT_V(8); PG8_WAIT_L(0); PG8_BAR; PG8_MMA(1, 0, At, B0); PG8_MMA(1, 1, At, B1); PG8_BAR; PG8_SCHED;
.LBB0_230:
	s_add_i32 s96, s40, 2
	s_cmp_gt_u32 s96, 7
	s_cselect_b32 s46, 0x600, 0
	s_cmp_gt_u32 s96, 5
	s_cselect_b32 s8, 0x600, 0
	s_add_u32 s8, s88, s8
	s_addc_u32 s9, s89, 0
	s_add_u32 s8, s8, 0x100
	s_addc_u32 s9, s9, 0
	s_add_i32 s13, 0, 0x10000
	v_add_u32_e32 v142, s13, v210
	v_add_u32_e32 v158, s15, v210
	ds_read_b128 v[130:133], v142
	ds_read_b128 v[134:137], v142 offset:1024
	ds_read_b128 v[138:141], v142 offset:2048
	ds_read_b128 v[142:145], v142 offset:3072
	ds_read_b128 v[146:149], v158
	ds_read_b128 v[150:153], v158 offset:1024
	ds_read_b128 v[154:157], v158 offset:2048
	ds_read_b128 v[158:161], v158 offset:3072
	s_cmp_eq_u32 s40, 12
	s_cselect_b32 s40, s87, vcc_lo
	s_cselect_b32 s91, s83, s9
	s_cselect_b32 s90, s82, s8
	s_cselect_b32 s41, s81, vcc_hi
	v_lshl_add_u64 v[212:213], s[88:89], 0, v[190:191]
	v_lshl_add_u64 v[212:213], v[212:213], 0, s[46:47]
	s_add_i32 m0, s19, 0xc000
	ds_read_b128 v[162:165], v211
	ds_read_b128 v[166:169], v211 offset:1024
	ds_read_b128 v[170:173], v211 offset:2048
	ds_read_b128 v[174:177], v211 offset:3072
	ds_read_b128 v[178:181], v211 offset:4096
	ds_read_b128 v[182:185], v211 offset:5120
	ds_read_b128 v[202:205], v211 offset:6144
	ds_read_b128 v[206:209], v211 offset:7168
	global_load_lds_dwordx4 v[212:213], off
	v_lshl_add_u64 v[212:213], s[88:89], 0, v[192:193]
	v_lshl_add_u64 v[212:213], v[212:213], 0, s[46:47]
	s_add_i32 m0, s19, 0xe000
	s_nop 0
	global_load_lds_dwordx4 v[212:213], off
	s_waitcnt vmcnt(8)
	s_waitcnt lgkmcnt(0)
	s_barrier
	s_setprio 1
	v_mfma_f32_16x16x32_bf16 v[126:129], v[130:133], v[162:165], v[126:129]
	v_mfma_f32_16x16x32_bf16 v[122:125], v[138:141], v[162:165], v[122:125]
	v_mfma_f32_16x16x32_bf16 v[108:111], v[130:133], v[170:173], v[108:111]
	v_mfma_f32_16x16x32_bf16 v[104:107], v[138:141], v[170:173], v[104:107]
	v_mfma_f32_16x16x32_bf16 v[92:95], v[130:133], v[178:181], v[92:95]
	v_mfma_f32_16x16x32_bf16 v[88:91], v[138:141], v[178:181], v[88:91]
	v_mfma_f32_16x16x32_bf16 v[76:79], v[130:133], v[202:205], v[76:79]
	v_mfma_f32_16x16x32_bf16 v[72:75], v[138:141], v[202:205], v[72:75]
	v_mfma_f32_16x16x32_bf16 v[126:129], v[134:137], v[166:169], v[126:129]
	v_mfma_f32_16x16x32_bf16 v[122:125], v[142:145], v[166:169], v[122:125]
	v_mfma_f32_16x16x32_bf16 v[108:111], v[134:137], v[174:177], v[108:111]
	v_mfma_f32_16x16x32_bf16 v[104:107], v[142:145], v[174:177], v[104:107]
	v_mfma_f32_16x16x32_bf16 v[92:95], v[134:137], v[182:185], v[92:95]
	v_mfma_f32_16x16x32_bf16 v[88:91], v[142:145], v[182:185], v[88:91]
	v_mfma_f32_16x16x32_bf16 v[76:79], v[134:137], v[206:209], v[76:79]
	v_mfma_f32_16x16x32_bf16 v[72:75], v[142:145], v[206:209], v[72:75]
	v_mfma_f32_16x16x32_bf16 v[118:121], v[146:149], v[162:165], v[118:121]
	v_mfma_f32_16x16x32_bf16 v[114:117], v[154:157], v[162:165], v[114:117]
	v_mfma_f32_16x16x32_bf16 v[100:103], v[146:149], v[170:173], v[100:103]
	v_mfma_f32_16x16x32_bf16 v[96:99], v[154:157], v[170:173], v[96:99]
	v_mfma_f32_16x16x32_bf16 v[84:87], v[146:149], v[178:181], v[84:87]
	v_mfma_f32_16x16x32_bf16 v[80:83], v[154:157], v[178:181], v[80:83]
	v_mfma_f32_16x16x32_bf16 v[68:71], v[146:149], v[202:205], v[68:71]
	v_mfma_f32_16x16x32_bf16 v[64:67], v[154:157], v[202:205], v[64:67]
	v_mfma_f32_16x16x32_bf16 v[118:121], v[150:153], v[166:169], v[118:121]
	v_mfma_f32_16x16x32_bf16 v[114:117], v[158:161], v[166:169], v[114:117]
	v_mfma_f32_16x16x32_bf16 v[100:103], v[150:153], v[174:177], v[100:103]
	v_mfma_f32_16x16x32_bf16 v[96:99], v[158:161], v[174:177], v[96:99]
	v_mfma_f32_16x16x32_bf16 v[84:87], v[150:153], v[182:185], v[84:87]
	v_mfma_f32_16x16x32_bf16 v[80:83], v[158:161], v[182:185], v[80:83]
	v_mfma_f32_16x16x32_bf16 v[68:71], v[150:153], v[206:209], v[68:71]
	v_mfma_f32_16x16x32_bf16 v[64:67], v[158:161], v[206:209], v[64:67]
	s_setprio 0
	s_barrier
	s_add_i32 s8, s13, s11
	v_lshl_add_u64 v[212:213], s[40:41], 0, v[112:113]
	s_mov_b32 m0, s8
	ds_read_b128 v[162:165], v211 offset:16384
	ds_read_b128 v[166:169], v211 offset:17408
	ds_read_b128 v[170:173], v211 offset:18432
	ds_read_b128 v[174:177], v211 offset:19456
	ds_read_b128 v[178:181], v211 offset:20480
	ds_read_b128 v[182:185], v211 offset:21504
	ds_read_b128 v[202:205], v211 offset:22528
	ds_read_b128 v[206:209], v211 offset:23552
	global_load_lds_dwordx4 v112, s[40:41]
	s_add_i32 m0, s8, 0x2000
	s_add_u32 s8, s40, 0x40000
	v_lshl_add_u64 v[214:215], s[40:41], 0, v[200:201]
	s_addc_u32 s9, s41, 0
	s_add_i32 s13, s15, s11
	global_load_lds_dwordx4 v200, s[40:41]
	s_mov_b32 m0, s13
	v_lshl_add_u64 v[236:237], s[90:91], 0, v[188:189]
	global_load_lds_dwordx4 v112, s[8:9]
	s_add_i32 m0, s13, 0x2000
	s_nop 0
	global_load_lds_dwordx4 v200, s[8:9]
	s_mov_b32 m0, s19
	s_nop 0
	global_load_lds_dwordx4 v186, s[90:91]
	s_mov_b32 m0, s23
	s_nop 0
	global_load_lds_dwordx4 v188, s[90:91]
	s_waitcnt vmcnt(8)
	s_waitcnt lgkmcnt(0)
	s_barrier
; #define PG8_STAGE(bufoff, gbase, voff) do { _Pragma("unroll") for (int _i = 0; _i < 2; ++_i) \
;         __builtin_amdgcn_global_load_lds((const unsigned*)((const char*)(gbase) + (voff)[_i]), (LAS unsigned*)(lds + (bufoff) + ldsw + _i * 8192), 16, 0, 0); } while (0)
; #define PG8_LDA(dst, b, h) do { _Pragma("unroll") for (int m = 0; m < 4; ++m) _Pragma("unroll") for (int k = 0; k < 2; ++k) dst[m][k] = *(const LAS bf16x8*)(lds + PG8_SA(b, h) + aoff + m * 2048 + k * 1024); } while (0)
; #define PG8_LDB(dst, b, h) do { _Pragma("unroll") for (int n = 0; n < 2; ++n) _Pragma("unroll") for (int k = 0; k < 2; ++k) dst[n][k] = *(const LAS bf16x8*)(lds + PG8_SB(b, h) + boff + n * 2048 + k * 1024); } while (0)
; #define PG8_MMA(ai, bj, At, Bt) do { __builtin_amdgcn_s_setprio(1); _Pragma("unroll") for (int m = 0; m < 4; ++m) _Pragma("unroll") for (int n = 0; n < 2; ++n) _Pragma("unroll") for (int k = 0; k < 2; ++k) \
;         acc[ai][bj][m][n] = __builtin_amdgcn_mfma_f32_16x16x32_bf16(Bt[n][k], At[m][k], acc[ai][bj][m][n], 0, 0, 0); __builtin_amdgcn_s_setprio(0); } while (0)
; #define PG8_WAIT_V(n) asm volatile("s_waitcnt vmcnt(" #n ")" ::: "memory")
; #define PG8_WAIT_L(n) asm volatile("s_waitcnt lgkmcnt(" #n ")" ::: "memory")
; #define PG8_BAR __builtin_amdgcn_s_barrier()
; #define PG8_SCHED __builtin_amdgcn_sched_barrier(0)
; template <class Epi>
; __device__ __forceinline__ void gemm_phase(LAS unsigned char* lds, const Gemm g, const StaticOrder& S, const Epi& E, const int tid) {
;     ...
;             PG8_WAIT_V(8); PG8_WAIT_L(0); PG8_BAR; PG8_MMA(1, 0, At, B0); PG8_MMA(1, 1, At, B1); PG8_BAR; PG8_SCHED;
;             PG8_LDB(B0, 1, 0); PG8_LDB(B1, 1, 1); PG8_SCHED; PG8_LDA(At, 1, 0); PG8_STAGE(PG8_SA(0, 1), a2 + hstepA, voffA);
;             PG8_WAIT_V(8); PG8_WAIT_L(0); PG8_BAR; PG8_MMA(0, 0, At, B0); PG8_MMA(0, 1, At, B1); PG8_BAR; PG8_SCHED;
	s_setprio 1
	v_mfma_f32_16x16x32_bf16 v[60:63], v[130:133], v[162:165], v[60:63]
	v_mfma_f32_16x16x32_bf16 v[56:59], v[138:141], v[162:165], v[56:59]
	v_mfma_f32_16x16x32_bf16 v[44:47], v[130:133], v[170:173], v[44:47]
	v_mfma_f32_16x16x32_bf16 v[40:43], v[138:141], v[170:173], v[40:43]
	v_mfma_f32_16x16x32_bf16 v[28:31], v[130:133], v[178:181], v[28:31]
	v_mfma_f32_16x16x32_bf16 v[24:27], v[138:141], v[178:181], v[24:27]
	v_mfma_f32_16x16x32_bf16 v[12:15], v[130:133], v[202:205], v[12:15]
	v_mfma_f32_16x16x32_bf16 v[8:11], v[138:141], v[202:205], v[8:11]
	v_mfma_f32_16x16x32_bf16 v[60:63], v[134:137], v[166:169], v[60:63]
	v_mfma_f32_16x16x32_bf16 v[56:59], v[142:145], v[166:169], v[56:59]
	v_mfma_f32_16x16x32_bf16 v[44:47], v[134:137], v[174:177], v[44:47]
	v_mfma_f32_16x16x32_bf16 v[40:43], v[142:145], v[174:177], v[40:43]
	v_mfma_f32_16x16x32_bf16 v[28:31], v[134:137], v[182:185], v[28:31]
	v_mfma_f32_16x16x32_bf16 v[24:27], v[142:145], v[182:185], v[24:27]
	v_mfma_f32_16x16x32_bf16 v[12:15], v[134:137], v[206:209], v[12:15]
	v_mfma_f32_16x16x32_bf16 v[8:11], v[142:145], v[206:209], v[8:11]
	v_mfma_f32_16x16x32_bf16 v[52:55], v[146:149], v[162:165], v[52:55]
	v_mfma_f32_16x16x32_bf16 v[48:51], v[154:157], v[162:165], v[48:51]
	v_mfma_f32_16x16x32_bf16 v[36:39], v[146:149], v[170:173], v[36:39]
	v_mfma_f32_16x16x32_bf16 v[32:35], v[154:157], v[170:173], v[32:35]
	v_mfma_f32_16x16x32_bf16 v[20:23], v[146:149], v[178:181], v[20:23]
	v_mfma_f32_16x16x32_bf16 v[16:19], v[154:157], v[178:181], v[16:19]
	v_mfma_f32_16x16x32_bf16 v[4:7], v[146:149], v[202:205], v[4:7]
	v_mfma_f32_16x16x32_bf16 v[0:3], v[154:157], v[202:205], v[0:3]
	v_mfma_f32_16x16x32_bf16 v[52:55], v[150:153], v[166:169], v[52:55]
	v_mfma_f32_16x16x32_bf16 v[48:51], v[158:161], v[166:169], v[48:51]
	v_mfma_f32_16x16x32_bf16 v[36:39], v[150:153], v[174:177], v[36:39]
	v_mfma_f32_16x16x32_bf16 v[32:35], v[158:161], v[174:177], v[32:35]
	v_mfma_f32_16x16x32_bf16 v[20:23], v[150:153], v[182:185], v[20:23]
	v_mfma_f32_16x16x32_bf16 v[16:19], v[158:161], v[182:185], v[16:19]
	v_mfma_f32_16x16x32_bf16 v[4:7], v[150:153], v[206:209], v[4:7]
	v_mfma_f32_16x16x32_bf16 v[0:3], v[158:161], v[206:209], v[0:3]
	s_setprio 0
	s_barrier
	s_add_i32 s13, 0, 0x18000
	s_add_i32 s31, 0, 0x1c000
	v_add_u32_e32 v142, s13, v210
	v_add_u32_e32 v158, s31, v210
	ds_read_b128 v[130:133], v142
	ds_read_b128 v[134:137], v142 offset:1024
	ds_read_b128 v[138:141], v142 offset:2048
	ds_read_b128 v[142:145], v142 offset:3072
	ds_read_b128 v[146:149], v158
	ds_read_b128 v[150:153], v158 offset:1024
	ds_read_b128 v[154:157], v158 offset:2048
	ds_read_b128 v[158:161], v158 offset:3072
	s_add_u32 s8, s90, 0x90000
	s_addc_u32 s9, s91, 0
	s_mov_b32 m0, s28
	ds_read_b128 v[162:165], v211 offset:32768
	ds_read_b128 v[166:169], v211 offset:33792
	ds_read_b128 v[170:173], v211 offset:34816
	ds_read_b128 v[174:177], v211 offset:35840
	ds_read_b128 v[178:181], v211 offset:36864
	ds_read_b128 v[182:185], v211 offset:37888
	ds_read_b128 v[202:205], v211 offset:38912
	ds_read_b128 v[206:209], v211 offset:39936
	global_load_lds_dwordx4 v186, s[8:9]
	v_lshl_add_u64 v[238:239], s[8:9], 0, v[188:189]
	s_mov_b32 m0, s30
	s_nop 0
	global_load_lds_dwordx4 v188, s[8:9]
	s_waitcnt vmcnt(8)
	s_waitcnt lgkmcnt(0)
	s_barrier
	s_setprio 1
	v_mfma_f32_16x16x32_bf16 v[126:129], v[130:133], v[162:165], v[126:129]
	v_mfma_f32_16x16x32_bf16 v[122:125], v[138:141], v[162:165], v[122:125]
	v_mfma_f32_16x16x32_bf16 v[108:111], v[130:133], v[170:173], v[108:111]
	v_mfma_f32_16x16x32_bf16 v[104:107], v[138:141], v[170:173], v[104:107]
	v_mfma_f32_16x16x32_bf16 v[92:95], v[130:133], v[178:181], v[92:95]
	v_mfma_f32_16x16x32_bf16 v[88:91], v[138:141], v[178:181], v[88:91]
	v_mfma_f32_16x16x32_bf16 v[76:79], v[130:133], v[202:205], v[76:79]
	v_mfma_f32_16x16x32_bf16 v[72:75], v[138:141], v[202:205], v[72:75]
	v_mfma_f32_16x16x32_bf16 v[126:129], v[134:137], v[166:169], v[126:129]
	v_mfma_f32_16x16x32_bf16 v[122:125], v[142:145], v[166:169], v[122:125]
	v_mfma_f32_16x16x32_bf16 v[108:111], v[134:137], v[174:177], v[108:111]
	v_mfma_f32_16x16x32_bf16 v[104:107], v[142:145], v[174:177], v[104:107]
	v_mfma_f32_16x16x32_bf16 v[92:95], v[134:137], v[182:185], v[92:95]
	v_mfma_f32_16x16x32_bf16 v[88:91], v[142:145], v[182:185], v[88:91]
	v_mfma_f32_16x16x32_bf16 v[76:79], v[134:137], v[206:209], v[76:79]
	v_mfma_f32_16x16x32_bf16 v[72:75], v[142:145], v[206:209], v[72:75]
	v_mfma_f32_16x16x32_bf16 v[118:121], v[146:149], v[162:165], v[118:121]
	v_mfma_f32_16x16x32_bf16 v[114:117], v[154:157], v[162:165], v[114:117]
	v_mfma_f32_16x16x32_bf16 v[100:103], v[146:149], v[170:173], v[100:103]
	v_mfma_f32_16x16x32_bf16 v[96:99], v[154:157], v[170:173], v[96:99]
	v_mfma_f32_16x16x32_bf16 v[84:87], v[146:149], v[178:181], v[84:87]
	v_mfma_f32_16x16x32_bf16 v[80:83], v[154:157], v[178:181], v[80:83]
	v_mfma_f32_16x16x32_bf16 v[68:71], v[146:149], v[202:205], v[68:71]
	v_mfma_f32_16x16x32_bf16 v[64:67], v[154:157], v[202:205], v[64:67]
	v_mfma_f32_16x16x32_bf16 v[118:121], v[150:153], v[166:169], v[118:121]
	v_mfma_f32_16x16x32_bf16 v[114:117], v[158:161], v[166:169], v[114:117]
	v_mfma_f32_16x16x32_bf16 v[100:103], v[150:153], v[174:177], v[100:103]
	v_mfma_f32_16x16x32_bf16 v[96:99], v[158:161], v[174:177], v[96:99]
	v_mfma_f32_16x16x32_bf16 v[84:87], v[150:153], v[182:185], v[84:87]
	v_mfma_f32_16x16x32_bf16 v[80:83], v[158:161], v[182:185], v[80:83]
	v_mfma_f32_16x16x32_bf16 v[68:71], v[150:153], v[206:209], v[68:71]
	v_mfma_f32_16x16x32_bf16 v[64:67], v[158:161], v[206:209], v[64:67]
	s_setprio 0
	s_barrier
; #define PG8_STAGE(bufoff, gbase, voff) do { _Pragma("unroll") for (int _i = 0; _i < 2; ++_i) \
;         __builtin_amdgcn_global_load_lds((const unsigned*)((const char*)(gbase) + (voff)[_i]), (LAS unsigned*)(lds + (bufoff) + ldsw + _i * 8192), 16, 0, 0); } while (0)
; #define PG8_LDA(dst, b, h) do { _Pragma("unroll") for (int m = 0; m < 4; ++m) _Pragma("unroll") for (int k = 0; k < 2; ++k) dst[m][k] = *(const LAS bf16x8*)(lds + PG8_SA(b, h) + aoff + m * 2048 + k * 1024); } while (0)
; #define PG8_MMA(ai, bj, At, Bt) do { __builtin_amdgcn_s_setprio(1); _Pragma("unroll") for (int m = 0; m < 4; ++m) _Pragma("unroll") for (int n = 0; n < 2; ++n) _Pragma("unroll") for (int k = 0; k < 2; ++k) \
;         acc[ai][bj][m][n] = __builtin_amdgcn_mfma_f32_16x16x32_bf16(Bt[n][k], At[m][k], acc[ai][bj][m][n], 0, 0, 0); __builtin_amdgcn_s_setprio(0); } while (0)
; #define PG8_WAIT_V(n) asm volatile("s_waitcnt vmcnt(" #n ")" ::: "memory")
; #define PG8_WAIT_L(n) asm volatile("s_waitcnt lgkmcnt(" #n ")" ::: "memory")
; #define PG8_BAR __builtin_amdgcn_s_barrier()
; #define PG8_SCHED __builtin_amdgcn_sched_barrier(0)
; template <class Epi>
; __device__ __forceinline__ void gemm_phase(LAS unsigned char* lds, const Gemm g, const StaticOrder& S, const Epi& E, const int tid) {
;     ...
;             PG8_LDA(At, 1, 1); PG8_STAGE(PG8_SB(1, 0), b3, voffB); PG8_STAGE(PG8_SB(1, 1), b3 + hstepB, voffB); PG8_STAGE(PG8_SA(1, 0), a3, voffA);
;             PG8_WAIT_V(8); PG8_WAIT_L(0); PG8_BAR; PG8_MMA(1, 0, At, B0); PG8_MMA(1, 1, At, B1); PG8_BAR; PG8_SCHED;
;         }
;         if (wr == 0) PG8_BAR;
	s_add_i32 s8, s13, s11
	s_add_u32 s100, s40, 0x80
	s_addc_u32 s101, s41, 0
	s_mov_b32 m0, s8
	ds_read_b128 v[162:165], v211 offset:49152
	ds_read_b128 v[166:169], v211 offset:50176
	ds_read_b128 v[170:173], v211 offset:51200
	ds_read_b128 v[174:177], v211 offset:52224
	ds_read_b128 v[178:181], v211 offset:53248
	ds_read_b128 v[182:185], v211 offset:54272
	ds_read_b128 v[202:205], v211 offset:55296
	ds_read_b128 v[206:209], v211 offset:56320
	global_load_lds_dwordx4 v112, s[100:101]
	s_add_i32 m0, s8, 0x2000
	s_add_u32 s8, s40, 0x40080
	v_lshl_add_u64 v[212:213], v[214:215], 0, s[24:25]
	s_addc_u32 s9, s41, 0
	s_add_i32 s13, s31, s11
	global_load_lds_dwordx4 v[212:213], off
	s_mov_b32 m0, s13
	s_nop 0
	global_load_lds_dwordx4 v112, s[8:9]
	s_add_i32 m0, s13, 0x2000
	s_nop 0
	global_load_lds_dwordx4 v200, s[8:9]
	s_add_u32 s100, s90, 0x80
	s_addc_u32 s101, s91, 0
	s_mov_b32 m0, s99
	s_nop 0
	global_load_lds_dwordx4 v186, s[100:101]
	s_add_u32 s100, s90, 0x80
	s_addc_u32 s101, s91, 0
	s_mov_b32 m0, s33
	s_nop 0
	global_load_lds_dwordx4 v188, s[100:101]
	s_waitcnt vmcnt(8)
	s_waitcnt lgkmcnt(0)
	s_barrier
	s_setprio 1
	v_mfma_f32_16x16x32_bf16 v[60:63], v[130:133], v[162:165], v[60:63]
	v_mfma_f32_16x16x32_bf16 v[56:59], v[138:141], v[162:165], v[56:59]
	v_mfma_f32_16x16x32_bf16 v[44:47], v[130:133], v[170:173], v[44:47]
	v_mfma_f32_16x16x32_bf16 v[40:43], v[138:141], v[170:173], v[40:43]
	v_mfma_f32_16x16x32_bf16 v[28:31], v[130:133], v[178:181], v[28:31]
	v_mfma_f32_16x16x32_bf16 v[24:27], v[138:141], v[178:181], v[24:27]
	v_mfma_f32_16x16x32_bf16 v[12:15], v[130:133], v[202:205], v[12:15]
	v_mfma_f32_16x16x32_bf16 v[8:11], v[138:141], v[202:205], v[8:11]
	v_mfma_f32_16x16x32_bf16 v[60:63], v[134:137], v[166:169], v[60:63]
	v_mfma_f32_16x16x32_bf16 v[56:59], v[142:145], v[166:169], v[56:59]
	v_mfma_f32_16x16x32_bf16 v[44:47], v[134:137], v[174:177], v[44:47]
	v_mfma_f32_16x16x32_bf16 v[40:43], v[142:145], v[174:177], v[40:43]
	v_mfma_f32_16x16x32_bf16 v[28:31], v[134:137], v[182:185], v[28:31]
	v_mfma_f32_16x16x32_bf16 v[24:27], v[142:145], v[182:185], v[24:27]
	v_mfma_f32_16x16x32_bf16 v[12:15], v[134:137], v[206:209], v[12:15]
	v_mfma_f32_16x16x32_bf16 v[8:11], v[142:145], v[206:209], v[8:11]
	v_mfma_f32_16x16x32_bf16 v[52:55], v[146:149], v[162:165], v[52:55]
	v_mfma_f32_16x16x32_bf16 v[48:51], v[154:157], v[162:165], v[48:51]
	v_mfma_f32_16x16x32_bf16 v[36:39], v[146:149], v[170:173], v[36:39]
	v_mfma_f32_16x16x32_bf16 v[32:35], v[154:157], v[170:173], v[32:35]
	v_mfma_f32_16x16x32_bf16 v[20:23], v[146:149], v[178:181], v[20:23]
	v_mfma_f32_16x16x32_bf16 v[16:19], v[154:157], v[178:181], v[16:19]
	v_mfma_f32_16x16x32_bf16 v[4:7], v[146:149], v[202:205], v[4:7]
	v_mfma_f32_16x16x32_bf16 v[0:3], v[154:157], v[202:205], v[0:3]
	v_mfma_f32_16x16x32_bf16 v[52:55], v[150:153], v[166:169], v[52:55]
	v_mfma_f32_16x16x32_bf16 v[48:51], v[158:161], v[166:169], v[48:51]
	v_mfma_f32_16x16x32_bf16 v[36:39], v[150:153], v[174:177], v[36:39]
	v_mfma_f32_16x16x32_bf16 v[32:35], v[158:161], v[174:177], v[32:35]
	v_mfma_f32_16x16x32_bf16 v[20:23], v[150:153], v[182:185], v[20:23]
	v_mfma_f32_16x16x32_bf16 v[16:19], v[158:161], v[182:185], v[16:19]
	v_mfma_f32_16x16x32_bf16 v[4:7], v[150:153], v[206:209], v[4:7]
	v_mfma_f32_16x16x32_bf16 v[0:3], v[158:161], v[206:209], v[0:3]
	s_setprio 0
	s_barrier
	s_add_u32 s88, s88, 0x100
	s_addc_u32 s89, s89, 0
	s_add_u32 vcc_lo, vcc_lo, 0x100
	s_addc_u32 vcc_hi, vcc_hi, 0
	s_cmp_gt_u32 s96, 13
	s_mov_b32 s40, s96
	s_cbranch_scc0 .LBB0_230
	s_and_b64 vcc, exec, s[44:45]
	s_cbranch_vccz .LBB0_233
	s_barrier

; #define PG8_STAGE(bufoff, gbase, voff) do { _Pragma("unroll") for (int _i = 0; _i < 2; ++_i) \
;         __builtin_amdgcn_global_load_lds((const unsigned*)((const char*)(gbase) + (voff)[_i]), (LAS unsigned*)(lds + (bufoff) + ldsw + _i * 8192), 16, 0, 0); } while (0)
; #define PG8_LDA(dst, b, h) do { _Pragma("unroll") for (int m = 0; m < 4; ++m) _Pragma("unroll") for (int k = 0; k < 2; ++k) dst[m][k] = *(const LAS bf16x8*)(lds + PG8_SA(b, h) + aoff + m * 2048 + k * 1024); } while (0)
; #define PG8_LDB(dst, b, h) do { _Pragma("unroll") for (int n = 0; n < 2; ++n) _Pragma("unroll") for (int k = 0; k < 2; ++k) dst[n][k] = *(const LAS bf16x8*)(lds + PG8_SB(b, h) + boff + n * 2048 + k * 1024); } while (0)
; #define PG8_MMA(ai, bj, At, Bt) do { __builtin_amdgcn_s_setprio(1); _Pragma("unroll") for (int m = 0; m < 4; ++m) _Pragma("unroll") for (int n = 0; n < 2; ++n) _Pragma("unroll") for (int k = 0; k < 2; ++k) \
;         acc[ai][bj][m][n] = __builtin_amdgcn_mfma_f32_16x16x32_bf16(Bt[n][k], At[m][k], acc[ai][bj][m][n], 0, 0, 0); __builtin_amdgcn_s_setprio(0); } while (0)
; #define PG8_WAIT_V(n) asm volatile("s_waitcnt vmcnt(" #n ")" ::: "memory")
; #define PG8_WAIT_L(n) asm volatile("s_waitcnt lgkmcnt(" #n ")" ::: "memory")
; #define PG8_BAR __builtin_amdgcn_s_barrier()
; template <class Epi>
; __device__ __forceinline__ void gemm_phase(LAS unsigned char* lds, const Gemm g, const StaticOrder& S, const Epi& E, const int tid) {
;     ...
;         for (int t = 0; t < nt; t += 2) {
;             const bool last = (t == nt - 2);
;             const char* a1 = cA + (size_t)(t + 1) * kstep + ((t + 1) >= 8 ? xtra : 0);
;             const char* a2 = last ? nA : cA + (size_t)(t + 2) * kstep + ((t + 2) >= 8 ? xtra : 0); const char* b2 = last ? nB : cB + (size_t)(t + 2) * kstep;
;             const char* a3 = a2 + kstep; const char* b3 = b2 + kstep;
;             PG8_LDB(B0, 0, 0); PG8_LDB(B1, 0, 1); PG8_SCHED; PG8_LDA(At, 0, 0); PG8_STAGE(PG8_SA(1, 1), a1 + hstepA, voffA);
;             PG8_WAIT_V(8); PG8_WAIT_L(0); PG8_BAR; PG8_MMA(0, 0, At, B0); PG8_MMA(0, 1, At, B1); PG8_BAR; PG8_SCHED;
;             PG8_LDA(At, 0, 1); PG8_STAGE(PG8_SB(0, 0), b2, voffB); PG8_STAGE(PG8_SB(0, 1), b2 + hstepB, voffB); PG8_STAGE(PG8_SA(0, 0), a2, voffA);
;             PG8_WAIT_V(8); PG8_WAIT_L(0); PG8_BAR; PG8_MMA(1, 0, At, B0); PG8_MMA(1, 1, At, B1); PG8_BAR; PG8_SCHED;
.LBB0_268:
	s_add_u32 s8, s40, 0xfffc0080
	s_addc_u32 s9, s41, -1
	s_add_i32 s13, 0, 0x10000
	v_add_u32_e32 v162, s13, v167
	ds_read_b128 v[150:153], v162
	ds_read_b128 v[154:157], v162 offset:1024
	ds_read_b128 v[158:161], v162 offset:2048
	ds_read_b128 v[170:173], v162 offset:3072
	v_add_u32_e32 v162, s15, v167
	ds_read_b128 v[174:177], v162
	ds_read_b128 v[178:181], v162 offset:1024
	ds_read_b128 v[182:185], v162 offset:2048
	ds_read_b128 v[186:189], v162 offset:3072
	s_cmp_eq_u32 s85, 12
	s_cselect_b32 vcc_hi, s33, s9
	s_cselect_b32 vcc_lo, s36, s8
	s_cselect_b32 s95, s37, s57
	s_cselect_b32 s94, s45, s46
	s_add_i32 m0, s11, 0xc000
	ds_read_b128 v[190:193], v169
	ds_read_b128 v[200:203], v169 offset:1024
	ds_read_b128 v[204:207], v169 offset:2048
	ds_read_b128 v[208:211], v169 offset:3072
	ds_read_b128 v[212:215], v169 offset:4096
	ds_read_b128 v[234:237], v169 offset:5120
	ds_read_b128 v[238:241], v169 offset:6144
	ds_read_b128 v[242:245], v169 offset:7168
	global_load_lds_dwordx4 v146, s[40:41]
	s_add_i32 m0, s11, 0xe000
	s_nop 0
	global_load_lds_dwordx4 v148, s[40:41]
	s_waitcnt vmcnt(8)
	s_waitcnt lgkmcnt(0)
	s_barrier
	s_setprio 1
	v_mfma_f32_16x16x32_bf16 v[134:137], v[150:153], v[190:193], v[134:137]
	v_mfma_f32_16x16x32_bf16 v[130:133], v[158:161], v[190:193], v[130:133]
	v_mfma_f32_16x16x32_bf16 v[118:121], v[150:153], v[204:207], v[118:121]
	v_mfma_f32_16x16x32_bf16 v[114:117], v[158:161], v[204:207], v[114:117]
	v_mfma_f32_16x16x32_bf16 v[100:103], v[150:153], v[212:215], v[100:103]
	v_mfma_f32_16x16x32_bf16 v[96:99], v[158:161], v[212:215], v[96:99]
	v_mfma_f32_16x16x32_bf16 v[84:87], v[150:153], v[238:241], v[84:87]
	v_mfma_f32_16x16x32_bf16 v[80:83], v[158:161], v[238:241], v[80:83]
	v_mfma_f32_16x16x32_bf16 v[134:137], v[154:157], v[200:203], v[134:137]
	v_mfma_f32_16x16x32_bf16 v[130:133], v[170:173], v[200:203], v[130:133]
	v_mfma_f32_16x16x32_bf16 v[118:121], v[154:157], v[208:211], v[118:121]
	v_mfma_f32_16x16x32_bf16 v[114:117], v[170:173], v[208:211], v[114:117]
	v_mfma_f32_16x16x32_bf16 v[100:103], v[154:157], v[234:237], v[100:103]
	v_mfma_f32_16x16x32_bf16 v[96:99], v[170:173], v[234:237], v[96:99]
	v_mfma_f32_16x16x32_bf16 v[84:87], v[154:157], v[242:245], v[84:87]
	v_mfma_f32_16x16x32_bf16 v[80:83], v[170:173], v[242:245], v[80:83]
	v_mfma_f32_16x16x32_bf16 v[126:129], v[174:177], v[190:193], v[126:129]
	v_mfma_f32_16x16x32_bf16 v[122:125], v[182:185], v[190:193], v[122:125]
	v_mfma_f32_16x16x32_bf16 v[108:111], v[174:177], v[204:207], v[108:111]
	v_mfma_f32_16x16x32_bf16 v[104:107], v[182:185], v[204:207], v[104:107]
	v_mfma_f32_16x16x32_bf16 v[92:95], v[174:177], v[212:215], v[92:95]
	v_mfma_f32_16x16x32_bf16 v[88:91], v[182:185], v[212:215], v[88:91]
	v_mfma_f32_16x16x32_bf16 v[76:79], v[174:177], v[238:241], v[76:79]
	v_mfma_f32_16x16x32_bf16 v[72:75], v[182:185], v[238:241], v[72:75]
	v_mfma_f32_16x16x32_bf16 v[126:129], v[178:181], v[200:203], v[126:129]
	v_mfma_f32_16x16x32_bf16 v[122:125], v[186:189], v[200:203], v[122:125]
	v_mfma_f32_16x16x32_bf16 v[108:111], v[178:181], v[208:211], v[108:111]
	v_mfma_f32_16x16x32_bf16 v[104:107], v[186:189], v[208:211], v[104:107]
	v_mfma_f32_16x16x32_bf16 v[92:95], v[178:181], v[234:237], v[92:95]
	v_mfma_f32_16x16x32_bf16 v[88:91], v[186:189], v[234:237], v[88:91]
	v_mfma_f32_16x16x32_bf16 v[76:79], v[178:181], v[242:245], v[76:79]
	v_mfma_f32_16x16x32_bf16 v[72:75], v[186:189], v[242:245], v[72:75]
	s_setprio 0
	s_barrier
	s_add_i32 s8, s13, s81
	s_mov_b32 m0, s8
	ds_read_b128 v[190:193], v169 offset:16384
	ds_read_b128 v[200:203], v169 offset:17408
	ds_read_b128 v[204:207], v169 offset:18432
	ds_read_b128 v[208:211], v169 offset:19456
	ds_read_b128 v[212:215], v169 offset:20480
	ds_read_b128 v[234:237], v169 offset:21504
	ds_read_b128 v[238:241], v169 offset:22528
	ds_read_b128 v[242:245], v169 offset:23552
	global_load_lds_dwordx4 v112, s[94:95]
	s_add_i32 m0, s8, 0x2000
	s_add_u32 s8, s94, 0x40000
	v_lshl_add_u64 v[228:229], s[94:95], 0, v[142:143]
	s_addc_u32 s9, s95, 0
	s_add_i32 s13, s15, s81
	global_load_lds_dwordx4 v142, s[94:95]
	s_mov_b32 m0, s13
	s_nop 0
	global_load_lds_dwordx4 v112, s[8:9]
	s_add_i32 m0, s13, 0x2000
	s_nop 0
	global_load_lds_dwordx4 v142, s[8:9]
	s_mov_b32 m0, s11
	s_nop 0
	global_load_lds_dwordx4 v138, vcc
	s_mov_b32 m0, s19
	s_nop 0
	global_load_lds_dwordx4 v140, vcc
	s_waitcnt vmcnt(8)
	s_waitcnt lgkmcnt(0)
	s_barrier
	s_setprio 1
	v_mfma_f32_16x16x32_bf16 v[68:71], v[150:153], v[190:193], v[68:71]
	v_mfma_f32_16x16x32_bf16 v[64:67], v[158:161], v[190:193], v[64:67]
	v_mfma_f32_16x16x32_bf16 v[52:55], v[150:153], v[204:207], v[52:55]
	v_mfma_f32_16x16x32_bf16 v[48:51], v[158:161], v[204:207], v[48:51]
	v_mfma_f32_16x16x32_bf16 v[36:39], v[150:153], v[212:215], v[36:39]
	v_mfma_f32_16x16x32_bf16 v[32:35], v[158:161], v[212:215], v[32:35]
	v_mfma_f32_16x16x32_bf16 v[20:23], v[150:153], v[238:241], v[20:23]
	v_mfma_f32_16x16x32_bf16 v[16:19], v[158:161], v[238:241], v[16:19]
	v_mfma_f32_16x16x32_bf16 v[68:71], v[154:157], v[200:203], v[68:71]
	v_mfma_f32_16x16x32_bf16 v[64:67], v[170:173], v[200:203], v[64:67]
	v_mfma_f32_16x16x32_bf16 v[52:55], v[154:157], v[208:211], v[52:55]
	v_mfma_f32_16x16x32_bf16 v[48:51], v[170:173], v[208:211], v[48:51]
	v_mfma_f32_16x16x32_bf16 v[36:39], v[154:157], v[234:237], v[36:39]
	v_mfma_f32_16x16x32_bf16 v[32:35], v[170:173], v[234:237], v[32:35]
	v_mfma_f32_16x16x32_bf16 v[20:23], v[154:157], v[242:245], v[20:23]
	v_mfma_f32_16x16x32_bf16 v[16:19], v[170:173], v[242:245], v[16:19]
	v_mfma_f32_16x16x32_bf16 v[60:63], v[174:177], v[190:193], v[60:63]
	v_mfma_f32_16x16x32_bf16 v[56:59], v[182:185], v[190:193], v[56:59]
	v_mfma_f32_16x16x32_bf16 v[44:47], v[174:177], v[204:207], v[44:47]
	v_mfma_f32_16x16x32_bf16 v[40:43], v[182:185], v[204:207], v[40:43]
	v_mfma_f32_16x16x32_bf16 v[28:31], v[174:177], v[212:215], v[28:31]
	v_mfma_f32_16x16x32_bf16 v[24:27], v[182:185], v[212:215], v[24:27]
	v_mfma_f32_16x16x32_bf16 v[12:15], v[174:177], v[238:241], v[12:15]
	v_mfma_f32_16x16x32_bf16 v[8:11], v[182:185], v[238:241], v[8:11]
	v_mfma_f32_16x16x32_bf16 v[60:63], v[178:181], v[200:203], v[60:63]
	v_mfma_f32_16x16x32_bf16 v[56:59], v[186:189], v[200:203], v[56:59]
	v_mfma_f32_16x16x32_bf16 v[44:47], v[178:181], v[208:211], v[44:47]
	v_mfma_f32_16x16x32_bf16 v[40:43], v[186:189], v[208:211], v[40:43]
	v_mfma_f32_16x16x32_bf16 v[28:31], v[178:181], v[234:237], v[28:31]
	v_mfma_f32_16x16x32_bf16 v[24:27], v[186:189], v[234:237], v[24:27]
	v_mfma_f32_16x16x32_bf16 v[12:15], v[178:181], v[242:245], v[12:15]
	v_mfma_f32_16x16x32_bf16 v[8:11], v[186:189], v[242:245], v[8:11]
	s_setprio 0
	s_barrier
; #define PG8_STAGE(bufoff, gbase, voff) do { _Pragma("unroll") for (int _i = 0; _i < 2; ++_i) \
;         __builtin_amdgcn_global_load_lds((const unsigned*)((const char*)(gbase) + (voff)[_i]), (LAS unsigned*)(lds + (bufoff) + ldsw + _i * 8192), 16, 0, 0); } while (0)
; #define PG8_LDA(dst, b, h) do { _Pragma("unroll") for (int m = 0; m < 4; ++m) _Pragma("unroll") for (int k = 0; k < 2; ++k) dst[m][k] = *(const LAS bf16x8*)(lds + PG8_SA(b, h) + aoff + m * 2048 + k * 1024); } while (0)
; #define PG8_LDB(dst, b, h) do { _Pragma("unroll") for (int n = 0; n < 2; ++n) _Pragma("unroll") for (int k = 0; k < 2; ++k) dst[n][k] = *(const LAS bf16x8*)(lds + PG8_SB(b, h) + boff + n * 2048 + k * 1024); } while (0)
; #define PG8_MMA(ai, bj, At, Bt) do { __builtin_amdgcn_s_setprio(1); _Pragma("unroll") for (int m = 0; m < 4; ++m) _Pragma("unroll") for (int n = 0; n < 2; ++n) _Pragma("unroll") for (int k = 0; k < 2; ++k) \
;         acc[ai][bj][m][n] = __builtin_amdgcn_mfma_f32_16x16x32_bf16(Bt[n][k], At[m][k], acc[ai][bj][m][n], 0, 0, 0); __builtin_amdgcn_s_setprio(0); } while (0)
; #define PG8_WAIT_V(n) asm volatile("s_waitcnt vmcnt(" #n ")" ::: "memory")
; #define PG8_WAIT_L(n) asm volatile("s_waitcnt lgkmcnt(" #n ")" ::: "memory")
; #define PG8_BAR __builtin_amdgcn_s_barrier()
; #define PG8_SCHED __builtin_amdgcn_sched_barrier(0)
; template <class Epi>
; __device__ __forceinline__ void gemm_phase(LAS unsigned char* lds, const Gemm g, const StaticOrder& S, const Epi& E, const int tid) {
;     ...
;             PG8_LDB(B0, 1, 0); PG8_LDB(B1, 1, 1); PG8_SCHED; PG8_LDA(At, 1, 0); PG8_STAGE(PG8_SA(0, 1), a2 + hstepA, voffA);
;             PG8_WAIT_V(8); PG8_WAIT_L(0); PG8_BAR; PG8_MMA(0, 0, At, B0); PG8_MMA(0, 1, At, B1); PG8_BAR; PG8_SCHED;
;             PG8_LDA(At, 1, 1); PG8_STAGE(PG8_SB(1, 0), b3, voffB); PG8_STAGE(PG8_SB(1, 1), b3 + hstepB, voffB); PG8_STAGE(PG8_SA(1, 0), a3, voffA);
;             PG8_WAIT_V(8); PG8_WAIT_L(0); PG8_BAR; PG8_MMA(1, 0, At, B0); PG8_MMA(1, 1, At, B1); PG8_BAR; PG8_SCHED;
;         }
;         if (wr == 0) PG8_BAR;
	s_add_i32 s13, 0, 0x18000
	s_add_i32 s31, 0, 0x1c000
	v_add_u32_e32 v170, s13, v167
	v_add_u32_e32 v186, s31, v167
	ds_read_b128 v[150:153], v170
	ds_read_b128 v[154:157], v170 offset:1024
	ds_read_b128 v[158:161], v170 offset:2048
	ds_read_b128 v[170:173], v170 offset:3072
	ds_read_b128 v[174:177], v186
	ds_read_b128 v[178:181], v186 offset:1024
	ds_read_b128 v[182:185], v186 offset:2048
	ds_read_b128 v[186:189], v186 offset:3072
	s_add_u32 s8, vcc_lo, 0x40000
	s_addc_u32 s9, vcc_hi, 0
	s_mov_b32 m0, s98
	ds_read_b128 v[190:193], v169 offset:32768
	ds_read_b128 v[200:203], v169 offset:33792
	ds_read_b128 v[204:207], v169 offset:34816
	ds_read_b128 v[208:211], v169 offset:35840
	ds_read_b128 v[212:215], v169 offset:36864
	ds_read_b128 v[234:237], v169 offset:37888
	ds_read_b128 v[238:241], v169 offset:38912
	ds_read_b128 v[242:245], v169 offset:39936
	global_load_lds_dwordx4 v138, s[8:9]
	s_mov_b32 m0, s99
	s_nop 0
	global_load_lds_dwordx4 v140, s[8:9]
	s_waitcnt vmcnt(8)
	s_waitcnt lgkmcnt(0)
	s_barrier
	s_setprio 1
	v_mfma_f32_16x16x32_bf16 v[134:137], v[150:153], v[190:193], v[134:137]
	v_mfma_f32_16x16x32_bf16 v[130:133], v[158:161], v[190:193], v[130:133]
	v_mfma_f32_16x16x32_bf16 v[118:121], v[150:153], v[204:207], v[118:121]
	v_mfma_f32_16x16x32_bf16 v[114:117], v[158:161], v[204:207], v[114:117]
	v_mfma_f32_16x16x32_bf16 v[100:103], v[150:153], v[212:215], v[100:103]
	v_mfma_f32_16x16x32_bf16 v[96:99], v[158:161], v[212:215], v[96:99]
	v_mfma_f32_16x16x32_bf16 v[84:87], v[150:153], v[238:241], v[84:87]
	v_mfma_f32_16x16x32_bf16 v[80:83], v[158:161], v[238:241], v[80:83]
	v_mfma_f32_16x16x32_bf16 v[134:137], v[154:157], v[200:203], v[134:137]
	v_mfma_f32_16x16x32_bf16 v[130:133], v[170:173], v[200:203], v[130:133]
	v_mfma_f32_16x16x32_bf16 v[118:121], v[154:157], v[208:211], v[118:121]
	v_mfma_f32_16x16x32_bf16 v[114:117], v[170:173], v[208:211], v[114:117]
	v_mfma_f32_16x16x32_bf16 v[100:103], v[154:157], v[234:237], v[100:103]
	v_mfma_f32_16x16x32_bf16 v[96:99], v[170:173], v[234:237], v[96:99]
	v_mfma_f32_16x16x32_bf16 v[84:87], v[154:157], v[242:245], v[84:87]
	v_mfma_f32_16x16x32_bf16 v[80:83], v[170:173], v[242:245], v[80:83]
	v_mfma_f32_16x16x32_bf16 v[126:129], v[174:177], v[190:193], v[126:129]
	v_mfma_f32_16x16x32_bf16 v[122:125], v[182:185], v[190:193], v[122:125]
	v_mfma_f32_16x16x32_bf16 v[108:111], v[174:177], v[204:207], v[108:111]
	v_mfma_f32_16x16x32_bf16 v[104:107], v[182:185], v[204:207], v[104:107]
	v_mfma_f32_16x16x32_bf16 v[92:95], v[174:177], v[212:215], v[92:95]
	v_mfma_f32_16x16x32_bf16 v[88:91], v[182:185], v[212:215], v[88:91]
	v_mfma_f32_16x16x32_bf16 v[76:79], v[174:177], v[238:241], v[76:79]
	v_mfma_f32_16x16x32_bf16 v[72:75], v[182:185], v[238:241], v[72:75]
	v_mfma_f32_16x16x32_bf16 v[126:129], v[178:181], v[200:203], v[126:129]
	v_mfma_f32_16x16x32_bf16 v[122:125], v[186:189], v[200:203], v[122:125]
	v_mfma_f32_16x16x32_bf16 v[108:111], v[178:181], v[208:211], v[108:111]
	v_mfma_f32_16x16x32_bf16 v[104:107], v[186:189], v[208:211], v[104:107]
	v_mfma_f32_16x16x32_bf16 v[92:95], v[178:181], v[234:237], v[92:95]
	v_mfma_f32_16x16x32_bf16 v[88:91], v[186:189], v[234:237], v[88:91]
	v_mfma_f32_16x16x32_bf16 v[76:79], v[178:181], v[242:245], v[76:79]
	v_mfma_f32_16x16x32_bf16 v[72:75], v[186:189], v[242:245], v[72:75]
	s_setprio 0
	s_barrier
	s_add_i32 s8, s13, s81
	s_add_u32 s100, s94, 0x80
	s_addc_u32 s101, s95, 0
	s_mov_b32 m0, s8
	ds_read_b128 v[190:193], v169 offset:49152
	ds_read_b128 v[200:203], v169 offset:50176
	ds_read_b128 v[204:207], v169 offset:51200
	ds_read_b128 v[208:211], v169 offset:52224
	ds_read_b128 v[212:215], v169 offset:53248
	ds_read_b128 v[234:237], v169 offset:54272
	ds_read_b128 v[238:241], v169 offset:55296
	ds_read_b128 v[242:245], v169 offset:56320
	global_load_lds_dwordx4 v112, s[100:101]
	s_add_i32 m0, s8, 0x2000
	s_add_u32 s8, s94, 0x40080
	v_lshl_add_u64 v[162:163], v[228:229], 0, s[24:25]
	s_addc_u32 s9, s95, 0
	s_add_i32 s13, s31, s81
	global_load_lds_dwordx4 v[162:163], off
	s_mov_b32 m0, s13
	s_nop 0
	global_load_lds_dwordx4 v112, s[8:9]
	s_add_i32 m0, s13, 0x2000
	s_nop 0
	global_load_lds_dwordx4 v142, s[8:9]
	s_add_u32 s100, vcc_lo, 0x80
	s_addc_u32 s101, vcc_hi, 0
	s_mov_b32 m0, s38
	s_nop 0
	global_load_lds_dwordx4 v138, s[100:101]
	s_add_u32 s100, vcc_lo, 0x80
	s_addc_u32 s101, vcc_hi, 0
	s_mov_b32 m0, s39
	s_nop 0
	global_load_lds_dwordx4 v140, s[100:101]
	s_waitcnt vmcnt(8)
	s_waitcnt lgkmcnt(0)
	s_barrier
	s_setprio 1
	v_mfma_f32_16x16x32_bf16 v[68:71], v[150:153], v[190:193], v[68:71]
	v_mfma_f32_16x16x32_bf16 v[64:67], v[158:161], v[190:193], v[64:67]
	v_mfma_f32_16x16x32_bf16 v[52:55], v[150:153], v[204:207], v[52:55]
	v_mfma_f32_16x16x32_bf16 v[48:51], v[158:161], v[204:207], v[48:51]
	v_mfma_f32_16x16x32_bf16 v[36:39], v[150:153], v[212:215], v[36:39]
	v_mfma_f32_16x16x32_bf16 v[32:35], v[158:161], v[212:215], v[32:35]
	v_mfma_f32_16x16x32_bf16 v[20:23], v[150:153], v[238:241], v[20:23]
	v_mfma_f32_16x16x32_bf16 v[16:19], v[158:161], v[238:241], v[16:19]
	v_mfma_f32_16x16x32_bf16 v[68:71], v[154:157], v[200:203], v[68:71]
	v_mfma_f32_16x16x32_bf16 v[64:67], v[170:173], v[200:203], v[64:67]
	v_mfma_f32_16x16x32_bf16 v[52:55], v[154:157], v[208:211], v[52:55]
	v_mfma_f32_16x16x32_bf16 v[48:51], v[170:173], v[208:211], v[48:51]
	v_mfma_f32_16x16x32_bf16 v[36:39], v[154:157], v[234:237], v[36:39]
	v_mfma_f32_16x16x32_bf16 v[32:35], v[170:173], v[234:237], v[32:35]
	v_mfma_f32_16x16x32_bf16 v[20:23], v[154:157], v[242:245], v[20:23]
	v_mfma_f32_16x16x32_bf16 v[16:19], v[170:173], v[242:245], v[16:19]
	v_mfma_f32_16x16x32_bf16 v[60:63], v[174:177], v[190:193], v[60:63]
	v_mfma_f32_16x16x32_bf16 v[56:59], v[182:185], v[190:193], v[56:59]
	v_mfma_f32_16x16x32_bf16 v[44:47], v[174:177], v[204:207], v[44:47]
	v_mfma_f32_16x16x32_bf16 v[40:43], v[182:185], v[204:207], v[40:43]
	v_mfma_f32_16x16x32_bf16 v[28:31], v[174:177], v[212:215], v[28:31]
	v_mfma_f32_16x16x32_bf16 v[24:27], v[182:185], v[212:215], v[24:27]
	v_mfma_f32_16x16x32_bf16 v[12:15], v[174:177], v[238:241], v[12:15]
	v_mfma_f32_16x16x32_bf16 v[8:11], v[182:185], v[238:241], v[8:11]
	v_mfma_f32_16x16x32_bf16 v[60:63], v[178:181], v[200:203], v[60:63]
	v_mfma_f32_16x16x32_bf16 v[56:59], v[186:189], v[200:203], v[56:59]
	v_mfma_f32_16x16x32_bf16 v[44:47], v[178:181], v[208:211], v[44:47]
	v_mfma_f32_16x16x32_bf16 v[40:43], v[186:189], v[208:211], v[40:43]
	v_mfma_f32_16x16x32_bf16 v[28:31], v[178:181], v[234:237], v[28:31]
	v_mfma_f32_16x16x32_bf16 v[24:27], v[186:189], v[234:237], v[24:27]
	v_mfma_f32_16x16x32_bf16 v[12:15], v[178:181], v[242:245], v[12:15]
	v_mfma_f32_16x16x32_bf16 v[8:11], v[186:189], v[242:245], v[8:11]
	s_setprio 0
	s_barrier
	s_add_i32 s85, s85, 2
	s_add_u32 s40, s40, 0x100
	s_addc_u32 s41, s41, 0
	s_add_u32 s46, s46, 0x100
	s_addc_u32 s57, s57, 0
	s_cmp_gt_u32 s85, 13
	s_cbranch_scc0 .LBB0_268
	s_and_b64 vcc, exec, s[82:83]
	s_cbranch_vccz .LBB0_271
	s_barrier

; #define PG8_STAGE(bufoff, gbase, voff) do { _Pragma("unroll") for (int _i = 0; _i < 2; ++_i) \
;         __builtin_amdgcn_global_load_lds((const unsigned*)((const char*)(gbase) + (voff)[_i]), (LAS unsigned*)(lds + (bufoff) + ldsw + _i * 8192), 16, 0, 0); } while (0)
; #define PG8_LDA(dst, b, h) do { _Pragma("unroll") for (int m = 0; m < 4; ++m) _Pragma("unroll") for (int k = 0; k < 2; ++k) dst[m][k] = *(const LAS bf16x8*)(lds + PG8_SA(b, h) + aoff + m * 2048 + k * 1024); } while (0)
; #define PG8_LDB(dst, b, h) do { _Pragma("unroll") for (int n = 0; n < 2; ++n) _Pragma("unroll") for (int k = 0; k < 2; ++k) dst[n][k] = *(const LAS bf16x8*)(lds + PG8_SB(b, h) + boff + n * 2048 + k * 1024); } while (0)
; #define PG8_MMA(ai, bj, At, Bt) do { __builtin_amdgcn_s_setprio(1); _Pragma("unroll") for (int m = 0; m < 4; ++m) _Pragma("unroll") for (int n = 0; n < 2; ++n) _Pragma("unroll") for (int k = 0; k < 2; ++k) \
;         acc[ai][bj][m][n] = __builtin_amdgcn_mfma_f32_16x16x32_bf16(Bt[n][k], At[m][k], acc[ai][bj][m][n], 0, 0, 0); __builtin_amdgcn_s_setprio(0); } while (0)
; #define PG8_WAIT_V(n) asm volatile("s_waitcnt vmcnt(" #n ")" ::: "memory")
; #define PG8_WAIT_L(n) asm volatile("s_waitcnt lgkmcnt(" #n ")" ::: "memory")
; #define PG8_BAR __builtin_amdgcn_s_barrier()
; template <class Epi>
; __device__ __forceinline__ void gemm_phase(LAS unsigned char* lds, const Gemm g, const StaticOrder& S, const Epi& E, const int tid) {
;     ...
;         for (int t = 0; t < nt; t += 2) {
;             const bool last = (t == nt - 2);
;             const char* a1 = cA + (size_t)(t + 1) * kstep + ((t + 1) >= 8 ? xtra : 0);
;             const char* a2 = last ? nA : cA + (size_t)(t + 2) * kstep + ((t + 2) >= 8 ? xtra : 0); const char* b2 = last ? nB : cB + (size_t)(t + 2) * kstep;
;             const char* a3 = a2 + kstep; const char* b3 = b2 + kstep;
;             PG8_LDB(B0, 0, 0); PG8_LDB(B1, 0, 1); PG8_SCHED; PG8_LDA(At, 0, 0); PG8_STAGE(PG8_SA(1, 1), a1 + hstepA, voffA);
;             PG8_WAIT_V(8); PG8_WAIT_L(0); PG8_BAR; PG8_MMA(0, 0, At, B0); PG8_MMA(0, 1, At, B1); PG8_BAR; PG8_SCHED;
;             PG8_LDA(At, 0, 1); PG8_STAGE(PG8_SB(0, 0), b2, voffB); PG8_STAGE(PG8_SB(0, 1), b2 + hstepB, voffB); PG8_STAGE(PG8_SA(0, 0), a2, voffA);
;             PG8_WAIT_V(8); PG8_WAIT_L(0); PG8_BAR; PG8_MMA(1, 0, At, B0); PG8_MMA(1, 1, At, B1); PG8_BAR; PG8_SCHED;
.LBB0_356:
	s_add_u32 s8, s42, 0xfffc0080
	s_addc_u32 s9, s43, -1
	s_add_i32 s13, 0, 0x10000
	v_add_u32_e32 v168, s13, v161
	v_add_u32_e32 v184, s15, v161
	ds_read_b128 v[150:153], v168
	ds_read_b128 v[154:157], v168 offset:1024
	ds_read_b128 v[164:167], v168 offset:2048
	ds_read_b128 v[168:171], v168 offset:3072
	ds_read_b128 v[172:175], v184
	ds_read_b128 v[176:179], v184 offset:1024
	ds_read_b128 v[180:183], v184 offset:2048
	ds_read_b128 v[184:187], v184 offset:3072
	s_cmp_eq_u32 s97, 12
	s_cselect_b32 s95, s98, s9
	s_cselect_b32 s94, s99, s8
	s_cselect_b32 s93, s83, s96
	s_cselect_b32 s92, vcc_lo, vcc_hi
	s_add_i32 m0, s19, 0xc000
	ds_read_b128 v[188:191], v163
	ds_read_b128 v[200:203], v163 offset:1024
	ds_read_b128 v[204:207], v163 offset:2048
	ds_read_b128 v[208:211], v163 offset:3072
	ds_read_b128 v[212:215], v163 offset:4096
	ds_read_b128 v[234:237], v163 offset:5120
	ds_read_b128 v[238:241], v163 offset:6144
	ds_read_b128 v[242:245], v163 offset:7168
	global_load_lds_dwordx4 v146, s[42:43]
	s_add_i32 m0, s19, 0xe000
	s_nop 0
	global_load_lds_dwordx4 v148, s[42:43]
	s_waitcnt vmcnt(8)
	s_waitcnt lgkmcnt(0)
	s_barrier
	s_setprio 1
	v_mfma_f32_16x16x32_bf16 v[134:137], v[150:153], v[188:191], v[134:137]
	v_mfma_f32_16x16x32_bf16 v[130:133], v[164:167], v[188:191], v[130:133]
	v_mfma_f32_16x16x32_bf16 v[122:125], v[150:153], v[204:207], v[122:125]
	v_mfma_f32_16x16x32_bf16 v[114:117], v[164:167], v[204:207], v[114:117]
	v_mfma_f32_16x16x32_bf16 v[104:107], v[150:153], v[212:215], v[104:107]
	v_mfma_f32_16x16x32_bf16 v[96:99], v[164:167], v[212:215], v[96:99]
	v_mfma_f32_16x16x32_bf16 v[88:91], v[150:153], v[238:241], v[88:91]
	v_mfma_f32_16x16x32_bf16 v[80:83], v[164:167], v[238:241], v[80:83]
	v_mfma_f32_16x16x32_bf16 v[134:137], v[154:157], v[200:203], v[134:137]
	v_mfma_f32_16x16x32_bf16 v[130:133], v[168:171], v[200:203], v[130:133]
	v_mfma_f32_16x16x32_bf16 v[122:125], v[154:157], v[208:211], v[122:125]
	v_mfma_f32_16x16x32_bf16 v[114:117], v[168:171], v[208:211], v[114:117]
	v_mfma_f32_16x16x32_bf16 v[104:107], v[154:157], v[234:237], v[104:107]
	v_mfma_f32_16x16x32_bf16 v[96:99], v[168:171], v[234:237], v[96:99]
	v_mfma_f32_16x16x32_bf16 v[88:91], v[154:157], v[242:245], v[88:91]
	v_mfma_f32_16x16x32_bf16 v[80:83], v[168:171], v[242:245], v[80:83]
	v_mfma_f32_16x16x32_bf16 v[126:129], v[172:175], v[188:191], v[126:129]
	v_mfma_f32_16x16x32_bf16 v[118:121], v[180:183], v[188:191], v[118:121]
	v_mfma_f32_16x16x32_bf16 v[108:111], v[172:175], v[204:207], v[108:111]
	v_mfma_f32_16x16x32_bf16 v[100:103], v[180:183], v[204:207], v[100:103]
	v_mfma_f32_16x16x32_bf16 v[92:95], v[172:175], v[212:215], v[92:95]
	v_mfma_f32_16x16x32_bf16 v[84:87], v[180:183], v[212:215], v[84:87]
	v_mfma_f32_16x16x32_bf16 v[76:79], v[172:175], v[238:241], v[76:79]
	v_mfma_f32_16x16x32_bf16 v[72:75], v[180:183], v[238:241], v[72:75]
	v_mfma_f32_16x16x32_bf16 v[126:129], v[176:179], v[200:203], v[126:129]
	v_mfma_f32_16x16x32_bf16 v[118:121], v[184:187], v[200:203], v[118:121]
	v_mfma_f32_16x16x32_bf16 v[108:111], v[176:179], v[208:211], v[108:111]
	v_mfma_f32_16x16x32_bf16 v[100:103], v[184:187], v[208:211], v[100:103]
	v_mfma_f32_16x16x32_bf16 v[92:95], v[176:179], v[234:237], v[92:95]
	v_mfma_f32_16x16x32_bf16 v[84:87], v[184:187], v[234:237], v[84:87]
	v_mfma_f32_16x16x32_bf16 v[76:79], v[176:179], v[242:245], v[76:79]
	v_mfma_f32_16x16x32_bf16 v[72:75], v[184:187], v[242:245], v[72:75]
	s_setprio 0
	s_barrier
	s_add_i32 s8, s13, s17
	s_mov_b32 m0, s8
	ds_read_b128 v[188:191], v163 offset:16384
	ds_read_b128 v[200:203], v163 offset:17408
	ds_read_b128 v[204:207], v163 offset:18432
	ds_read_b128 v[208:211], v163 offset:19456
	ds_read_b128 v[212:215], v163 offset:20480
	ds_read_b128 v[234:237], v163 offset:21504
	ds_read_b128 v[238:241], v163 offset:22528
	ds_read_b128 v[242:245], v163 offset:23552
	global_load_lds_dwordx4 v112, s[92:93]
	s_add_i32 m0, s8, 0x2000
	s_add_u32 s8, s92, 0x40000
	v_lshl_add_u64 v[246:247], s[92:93], 0, v[142:143]
	s_addc_u32 s9, s93, 0
	s_add_i32 s13, s15, s17
	global_load_lds_dwordx4 v142, s[92:93]
	s_mov_b32 m0, s13
	s_nop 0
	global_load_lds_dwordx4 v112, s[8:9]
	s_add_i32 m0, s13, 0x2000
	s_nop 0
	global_load_lds_dwordx4 v142, s[8:9]
	s_mov_b32 m0, s19
	s_nop 0
	global_load_lds_dwordx4 v138, s[94:95]
	s_mov_b32 m0, s23
	s_nop 0
	global_load_lds_dwordx4 v140, s[94:95]
	s_waitcnt vmcnt(8)
	s_waitcnt lgkmcnt(0)
	s_barrier
	s_setprio 1
	v_mfma_f32_16x16x32_bf16 v[68:71], v[150:153], v[188:191], v[68:71]
	v_mfma_f32_16x16x32_bf16 v[64:67], v[164:167], v[188:191], v[64:67]
	v_mfma_f32_16x16x32_bf16 v[56:59], v[150:153], v[204:207], v[56:59]
	v_mfma_f32_16x16x32_bf16 v[48:51], v[164:167], v[204:207], v[48:51]
	v_mfma_f32_16x16x32_bf16 v[40:43], v[150:153], v[212:215], v[40:43]
	v_mfma_f32_16x16x32_bf16 v[32:35], v[164:167], v[212:215], v[32:35]
	v_mfma_f32_16x16x32_bf16 v[24:27], v[150:153], v[238:241], v[24:27]
	v_mfma_f32_16x16x32_bf16 v[16:19], v[164:167], v[238:241], v[16:19]
	v_mfma_f32_16x16x32_bf16 v[68:71], v[154:157], v[200:203], v[68:71]
	v_mfma_f32_16x16x32_bf16 v[64:67], v[168:171], v[200:203], v[64:67]
	v_mfma_f32_16x16x32_bf16 v[56:59], v[154:157], v[208:211], v[56:59]
	v_mfma_f32_16x16x32_bf16 v[48:51], v[168:171], v[208:211], v[48:51]
	v_mfma_f32_16x16x32_bf16 v[40:43], v[154:157], v[234:237], v[40:43]
	v_mfma_f32_16x16x32_bf16 v[32:35], v[168:171], v[234:237], v[32:35]
	v_mfma_f32_16x16x32_bf16 v[24:27], v[154:157], v[242:245], v[24:27]
	v_mfma_f32_16x16x32_bf16 v[16:19], v[168:171], v[242:245], v[16:19]
	v_mfma_f32_16x16x32_bf16 v[60:63], v[172:175], v[188:191], v[60:63]
	v_mfma_f32_16x16x32_bf16 v[52:55], v[180:183], v[188:191], v[52:55]
	v_mfma_f32_16x16x32_bf16 v[44:47], v[172:175], v[204:207], v[44:47]
	v_mfma_f32_16x16x32_bf16 v[36:39], v[180:183], v[204:207], v[36:39]
	v_mfma_f32_16x16x32_bf16 v[28:31], v[172:175], v[212:215], v[28:31]
	v_mfma_f32_16x16x32_bf16 v[20:23], v[180:183], v[212:215], v[20:23]
	v_mfma_f32_16x16x32_bf16 v[12:15], v[172:175], v[238:241], v[12:15]
	v_mfma_f32_16x16x32_bf16 v[8:11], v[180:183], v[238:241], v[8:11]
	v_mfma_f32_16x16x32_bf16 v[60:63], v[176:179], v[200:203], v[60:63]
	v_mfma_f32_16x16x32_bf16 v[52:55], v[184:187], v[200:203], v[52:55]
	v_mfma_f32_16x16x32_bf16 v[44:47], v[176:179], v[208:211], v[44:47]
	v_mfma_f32_16x16x32_bf16 v[36:39], v[184:187], v[208:211], v[36:39]
	v_mfma_f32_16x16x32_bf16 v[28:31], v[176:179], v[234:237], v[28:31]
	v_mfma_f32_16x16x32_bf16 v[20:23], v[184:187], v[234:237], v[20:23]
	v_mfma_f32_16x16x32_bf16 v[12:15], v[176:179], v[242:245], v[12:15]
	v_mfma_f32_16x16x32_bf16 v[8:11], v[184:187], v[242:245], v[8:11]
	s_setprio 0
	s_barrier
; #define PG8_STAGE(bufoff, gbase, voff) do { _Pragma("unroll") for (int _i = 0; _i < 2; ++_i) \
;         __builtin_amdgcn_global_load_lds((const unsigned*)((const char*)(gbase) + (voff)[_i]), (LAS unsigned*)(lds + (bufoff) + ldsw + _i * 8192), 16, 0, 0); } while (0)
; #define PG8_LDA(dst, b, h) do { _Pragma("unroll") for (int m = 0; m < 4; ++m) _Pragma("unroll") for (int k = 0; k < 2; ++k) dst[m][k] = *(const LAS bf16x8*)(lds + PG8_SA(b, h) + aoff + m * 2048 + k * 1024); } while (0)
; #define PG8_LDB(dst, b, h) do { _Pragma("unroll") for (int n = 0; n < 2; ++n) _Pragma("unroll") for (int k = 0; k < 2; ++k) dst[n][k] = *(const LAS bf16x8*)(lds + PG8_SB(b, h) + boff + n * 2048 + k * 1024); } while (0)
; #define PG8_MMA(ai, bj, At, Bt) do { __builtin_amdgcn_s_setprio(1); _Pragma("unroll") for (int m = 0; m < 4; ++m) _Pragma("unroll") for (int n = 0; n < 2; ++n) _Pragma("unroll") for (int k = 0; k < 2; ++k) \
;         acc[ai][bj][m][n] = __builtin_amdgcn_mfma_f32_16x16x32_bf16(Bt[n][k], At[m][k], acc[ai][bj][m][n], 0, 0, 0); __builtin_amdgcn_s_setprio(0); } while (0)
; #define PG8_WAIT_V(n) asm volatile("s_waitcnt vmcnt(" #n ")" ::: "memory")
; #define PG8_WAIT_L(n) asm volatile("s_waitcnt lgkmcnt(" #n ")" ::: "memory")
; #define PG8_BAR __builtin_amdgcn_s_barrier()
; #define PG8_SCHED __builtin_amdgcn_sched_barrier(0)
; template <class Epi>
; __device__ __forceinline__ void gemm_phase(LAS unsigned char* lds, const Gemm g, const StaticOrder& S, const Epi& E, const int tid) {
;     ...
;             PG8_LDB(B0, 1, 0); PG8_LDB(B1, 1, 1); PG8_SCHED; PG8_LDA(At, 1, 0); PG8_STAGE(PG8_SA(0, 1), a2 + hstepA, voffA);
;             PG8_WAIT_V(8); PG8_WAIT_L(0); PG8_BAR; PG8_MMA(0, 0, At, B0); PG8_MMA(0, 1, At, B1); PG8_BAR; PG8_SCHED;
;             PG8_LDA(At, 1, 1); PG8_STAGE(PG8_SB(1, 0), b3, voffB); PG8_STAGE(PG8_SB(1, 1), b3 + hstepB, voffB); PG8_STAGE(PG8_SA(1, 0), a3, voffA);
;             PG8_WAIT_V(8); PG8_WAIT_L(0); PG8_BAR; PG8_MMA(1, 0, At, B0); PG8_MMA(1, 1, At, B1); PG8_BAR; PG8_SCHED;
;         }
;         if (wr == 0) PG8_BAR;
	s_add_i32 s13, 0, 0x18000
	s_add_i32 s31, 0, 0x1c000
	v_add_u32_e32 v168, s13, v161
	v_add_u32_e32 v184, s31, v161
	ds_read_b128 v[150:153], v168
	ds_read_b128 v[154:157], v168 offset:1024
	ds_read_b128 v[164:167], v168 offset:2048
	ds_read_b128 v[168:171], v168 offset:3072
	ds_read_b128 v[172:175], v184
	ds_read_b128 v[176:179], v184 offset:1024
	ds_read_b128 v[180:183], v184 offset:2048
	ds_read_b128 v[184:187], v184 offset:3072
	s_add_u32 s8, s94, 0x40000
	s_addc_u32 s9, s95, 0
	s_mov_b32 m0, s28
	ds_read_b128 v[188:191], v163 offset:32768
	ds_read_b128 v[200:203], v163 offset:33792
	ds_read_b128 v[204:207], v163 offset:34816
	ds_read_b128 v[208:211], v163 offset:35840
	ds_read_b128 v[212:215], v163 offset:36864
	ds_read_b128 v[234:237], v163 offset:37888
	ds_read_b128 v[238:241], v163 offset:38912
	ds_read_b128 v[242:245], v163 offset:39936
	global_load_lds_dwordx4 v138, s[8:9]
	s_mov_b32 m0, s30
	s_nop 0
	global_load_lds_dwordx4 v140, s[8:9]
	s_waitcnt vmcnt(8)
	s_waitcnt lgkmcnt(0)
	s_barrier
	s_setprio 1
	v_mfma_f32_16x16x32_bf16 v[134:137], v[150:153], v[188:191], v[134:137]
	v_mfma_f32_16x16x32_bf16 v[130:133], v[164:167], v[188:191], v[130:133]
	v_mfma_f32_16x16x32_bf16 v[122:125], v[150:153], v[204:207], v[122:125]
	v_mfma_f32_16x16x32_bf16 v[114:117], v[164:167], v[204:207], v[114:117]
	v_mfma_f32_16x16x32_bf16 v[104:107], v[150:153], v[212:215], v[104:107]
	v_mfma_f32_16x16x32_bf16 v[96:99], v[164:167], v[212:215], v[96:99]
	v_mfma_f32_16x16x32_bf16 v[88:91], v[150:153], v[238:241], v[88:91]
	v_mfma_f32_16x16x32_bf16 v[80:83], v[164:167], v[238:241], v[80:83]
	v_mfma_f32_16x16x32_bf16 v[134:137], v[154:157], v[200:203], v[134:137]
	v_mfma_f32_16x16x32_bf16 v[130:133], v[168:171], v[200:203], v[130:133]
	v_mfma_f32_16x16x32_bf16 v[122:125], v[154:157], v[208:211], v[122:125]
	v_mfma_f32_16x16x32_bf16 v[114:117], v[168:171], v[208:211], v[114:117]
	v_mfma_f32_16x16x32_bf16 v[104:107], v[154:157], v[234:237], v[104:107]
	v_mfma_f32_16x16x32_bf16 v[96:99], v[168:171], v[234:237], v[96:99]
	v_mfma_f32_16x16x32_bf16 v[88:91], v[154:157], v[242:245], v[88:91]
	v_mfma_f32_16x16x32_bf16 v[80:83], v[168:171], v[242:245], v[80:83]
	v_mfma_f32_16x16x32_bf16 v[126:129], v[172:175], v[188:191], v[126:129]
	v_mfma_f32_16x16x32_bf16 v[118:121], v[180:183], v[188:191], v[118:121]
	v_mfma_f32_16x16x32_bf16 v[108:111], v[172:175], v[204:207], v[108:111]
	v_mfma_f32_16x16x32_bf16 v[100:103], v[180:183], v[204:207], v[100:103]
	v_mfma_f32_16x16x32_bf16 v[92:95], v[172:175], v[212:215], v[92:95]
	v_mfma_f32_16x16x32_bf16 v[84:87], v[180:183], v[212:215], v[84:87]
	v_mfma_f32_16x16x32_bf16 v[76:79], v[172:175], v[238:241], v[76:79]
	v_mfma_f32_16x16x32_bf16 v[72:75], v[180:183], v[238:241], v[72:75]
	v_mfma_f32_16x16x32_bf16 v[126:129], v[176:179], v[200:203], v[126:129]
	v_mfma_f32_16x16x32_bf16 v[118:121], v[184:187], v[200:203], v[118:121]
	v_mfma_f32_16x16x32_bf16 v[108:111], v[176:179], v[208:211], v[108:111]
	v_mfma_f32_16x16x32_bf16 v[100:103], v[184:187], v[208:211], v[100:103]
	v_mfma_f32_16x16x32_bf16 v[92:95], v[176:179], v[234:237], v[92:95]
	v_mfma_f32_16x16x32_bf16 v[84:87], v[184:187], v[234:237], v[84:87]
	v_mfma_f32_16x16x32_bf16 v[76:79], v[176:179], v[242:245], v[76:79]
	v_mfma_f32_16x16x32_bf16 v[72:75], v[184:187], v[242:245], v[72:75]
	s_setprio 0
	s_barrier
	s_add_i32 s8, s13, s17
	s_add_u32 s100, s92, 0x80
	s_addc_u32 s101, s93, 0
	s_mov_b32 m0, s8
	ds_read_b128 v[188:191], v163 offset:49152
	ds_read_b128 v[200:203], v163 offset:50176
	ds_read_b128 v[204:207], v163 offset:51200
	ds_read_b128 v[208:211], v163 offset:52224
	ds_read_b128 v[212:215], v163 offset:53248
	ds_read_b128 v[234:237], v163 offset:54272
	ds_read_b128 v[238:241], v163 offset:55296
	ds_read_b128 v[242:245], v163 offset:56320
	global_load_lds_dwordx4 v112, s[100:101]
	s_add_i32 m0, s8, 0x2000
	s_add_u32 s8, s92, 0x40080
	v_lshl_add_u64 v[192:193], v[246:247], 0, s[24:25]
	s_addc_u32 s9, s93, 0
	s_add_i32 s13, s31, s17
	global_load_lds_dwordx4 v[192:193], off
	s_mov_b32 m0, s13
	s_nop 0
	global_load_lds_dwordx4 v112, s[8:9]
	s_add_i32 m0, s13, 0x2000
	s_nop 0
	global_load_lds_dwordx4 v142, s[8:9]
	s_add_u32 s100, s94, 0x80
	s_addc_u32 s101, s95, 0
	s_mov_b32 m0, s36
	s_nop 0
	global_load_lds_dwordx4 v138, s[100:101]
	s_add_u32 s100, s94, 0x80
	s_addc_u32 s101, s95, 0
	s_mov_b32 m0, s37
	s_nop 0
	global_load_lds_dwordx4 v140, s[100:101]
	s_waitcnt vmcnt(8)
	s_waitcnt lgkmcnt(0)
	s_barrier
	s_setprio 1
	v_mfma_f32_16x16x32_bf16 v[68:71], v[150:153], v[188:191], v[68:71]
	v_mfma_f32_16x16x32_bf16 v[64:67], v[164:167], v[188:191], v[64:67]
	v_mfma_f32_16x16x32_bf16 v[56:59], v[150:153], v[204:207], v[56:59]
	v_mfma_f32_16x16x32_bf16 v[48:51], v[164:167], v[204:207], v[48:51]
	v_mfma_f32_16x16x32_bf16 v[40:43], v[150:153], v[212:215], v[40:43]
	v_mfma_f32_16x16x32_bf16 v[32:35], v[164:167], v[212:215], v[32:35]
	v_mfma_f32_16x16x32_bf16 v[24:27], v[150:153], v[238:241], v[24:27]
	v_mfma_f32_16x16x32_bf16 v[16:19], v[164:167], v[238:241], v[16:19]
	v_mfma_f32_16x16x32_bf16 v[68:71], v[154:157], v[200:203], v[68:71]
	v_mfma_f32_16x16x32_bf16 v[64:67], v[168:171], v[200:203], v[64:67]
	v_mfma_f32_16x16x32_bf16 v[56:59], v[154:157], v[208:211], v[56:59]
	v_mfma_f32_16x16x32_bf16 v[48:51], v[168:171], v[208:211], v[48:51]
	v_mfma_f32_16x16x32_bf16 v[40:43], v[154:157], v[234:237], v[40:43]
	v_mfma_f32_16x16x32_bf16 v[32:35], v[168:171], v[234:237], v[32:35]
	v_mfma_f32_16x16x32_bf16 v[24:27], v[154:157], v[242:245], v[24:27]
	v_mfma_f32_16x16x32_bf16 v[16:19], v[168:171], v[242:245], v[16:19]
	v_mfma_f32_16x16x32_bf16 v[60:63], v[172:175], v[188:191], v[60:63]
	v_mfma_f32_16x16x32_bf16 v[52:55], v[180:183], v[188:191], v[52:55]
	v_mfma_f32_16x16x32_bf16 v[44:47], v[172:175], v[204:207], v[44:47]
	v_mfma_f32_16x16x32_bf16 v[36:39], v[180:183], v[204:207], v[36:39]
	v_mfma_f32_16x16x32_bf16 v[28:31], v[172:175], v[212:215], v[28:31]
	v_mfma_f32_16x16x32_bf16 v[20:23], v[180:183], v[212:215], v[20:23]
	v_mfma_f32_16x16x32_bf16 v[12:15], v[172:175], v[238:241], v[12:15]
	v_mfma_f32_16x16x32_bf16 v[8:11], v[180:183], v[238:241], v[8:11]
	v_mfma_f32_16x16x32_bf16 v[60:63], v[176:179], v[200:203], v[60:63]
	v_mfma_f32_16x16x32_bf16 v[52:55], v[184:187], v[200:203], v[52:55]
	v_mfma_f32_16x16x32_bf16 v[44:47], v[176:179], v[208:211], v[44:47]
	v_mfma_f32_16x16x32_bf16 v[36:39], v[184:187], v[208:211], v[36:39]
	v_mfma_f32_16x16x32_bf16 v[28:31], v[176:179], v[234:237], v[28:31]
	v_mfma_f32_16x16x32_bf16 v[20:23], v[184:187], v[234:237], v[20:23]
	v_mfma_f32_16x16x32_bf16 v[12:15], v[176:179], v[242:245], v[12:15]
	v_mfma_f32_16x16x32_bf16 v[8:11], v[184:187], v[242:245], v[8:11]
	s_setprio 0
	s_barrier
	s_add_i32 s97, s97, 2
	s_add_u32 s42, s42, 0x100
	s_addc_u32 s43, s43, 0
	s_add_u32 vcc_hi, vcc_hi, 0x100
	s_addc_u32 s96, s96, 0
	s_cmp_gt_u32 s97, 13
	s_cbranch_scc0 .LBB0_356
	s_and_b64 vcc, exec, s[80:81]
	s_cbranch_vccz .LBB0_359
	s_barrier
